# selected-branch K and V^T blocks stored in MFMA lane order so each block load is one contiguous 1 KiB per instruction; forced-block cache fill loads issued together
# speedup vs baseline: 1.1001x; 1.0116x over previous
.LBB0_2001:
	s_waitcnt lgkmcnt(0)
	v_cndmask_b32_e64 v202, 1.0, v218, s[12:13]
	s_add_i32 s53, s80, -4
	s_mul_hi_u32 s51, s53, 0x900000
	s_mul_i32 s53, s53, 0x900000
	s_ashr_i32 s58, s58, 6
	v_pk_mul_f32 v[146:147], v[202:203], v[146:147] op_sel_hi:[0,1]
	v_pk_mul_f32 v[144:145], v[202:203], v[144:145] op_sel_hi:[0,1]
	v_pk_mul_f32 v[148:149], v[202:203], v[154:155] op_sel_hi:[0,1]
	v_pk_mul_f32 v[150:151], v[202:203], v[152:153] op_sel_hi:[0,1]
	s_mov_b64 s[12:13], -1
	s_and_b64 vcc, exec, s[84:85]
	s_cbranch_vccz .LBB0_2013
	s_mov_b64 s[86:87], -1
	s_mov_b64 s[12:13], 0
	s_cmp_lt_i32 s80, 7
	s_mov_b64 s[82:83], 0
	s_cbranch_scc1 .LBB0_2008
	s_cmp_eq_u32 s80, 7
	s_mov_b64 s[82:83], -1
	s_cbranch_scc0 .LBB0_2005
	v_mov_b32_e32 v154, 0
	v_cvt_pk_fp8_f32 v154, v144, v145
	v_mov_b32_e32 v155, 0
	v_cvt_pk_fp8_f32 v155, v150, v151
	s_add_i32 s60, s58, s30
	v_cvt_pk_fp8_f32 v154, v146, v147 op_sel:[0,0,1]
	s_ashr_i32 s61, s60, 31
	v_cvt_pk_fp8_f32 v155, v148, v149 op_sel:[0,0,1]
	s_lshl_b64 s[60:61], s[60:61], 12
	v_lshl_add_u64 v[152:153], v[178:179], 0, s[60:61]
	v_lshrrev_b32_e32 v252, 2, v152
	v_lshlrev_b32_e32 v253, 4, v152
	v_and_b32_e32 v252, 0xf0, v252
	v_and_b32_e32 v253, 0x300, v253
	v_and_b32_e32 v152, 0xfffffc0f, v152
	v_or3_b32 v152, v152, v252, v253
	v_lshrrev_b32_e32 v156, 8, v154
	global_store_byte v[152:153], v154, off
	global_store_byte v[152:153], v156, off offset:16
	global_store_byte_d16_hi v[152:153], v154, off offset:32
	v_lshrrev_b32_e32 v154, 24, v154
	global_store_byte v[152:153], v154, off offset:48
	global_store_byte v[152:153], v155, off offset:64
	v_lshrrev_b32_e32 v154, 8, v155
	global_store_byte v[152:153], v154, off offset:80
	global_store_byte_d16_hi v[152:153], v155, off offset:96
	v_lshrrev_b32_e32 v154, 24, v155
	global_store_byte v[152:153], v154, off offset:112
	s_mov_b64 s[82:83], 0

.LBB0_2011:
	v_mov_b32_e32 v154, 0
	v_mov_b32_e32 v155, 0
	v_cvt_pk_fp8_f32 v154, v144, v145
	v_cvt_pk_fp8_f32 v155, v150, v151
	v_lshlrev_b64 v[152:153], 6, v[152:153]
	v_lshl_add_u64 v[152:153], v[180:181], 0, v[152:153]
	v_cvt_pk_fp8_f32 v154, v146, v147 op_sel:[0,0,1]
	v_cvt_pk_fp8_f32 v155, v148, v149 op_sel:[0,0,1]
	v_lshrrev_b32_e32 v252, 2, v152
	v_lshlrev_b32_e32 v253, 4, v152
	v_and_b32_e32 v252, 0xf0, v252
	v_and_b32_e32 v253, 0x300, v253
	v_and_b32_e32 v152, 0xfffffc0f, v152
	v_or3_b32 v152, v152, v252, v253
	global_store_dwordx2 v[152:153], v[154:155], off sc1

.LBB0_2023:
	s_waitcnt vmcnt(0)
	v_mov_b32_e32 v128, v202
	v_mov_b32_e32 v129, v202
	v_mov_b32_e32 v203, v202
	v_pk_mul_f32 v[126:127], v[128:129], v[126:127]
	v_pk_mul_f32 v[122:123], v[128:129], v[122:123]
	v_cndmask_b32_e64 v128, 0, 1, s[84:85]
	v_pk_mul_f32 v[124:125], v[202:203], v[124:125]
	v_pk_mul_f32 v[120:121], v[202:203], v[120:121]
	v_cmp_ne_u32_e64 s[12:13], 1, v128
	s_andn2_b64 vcc, exec, s[84:85]
	s_mov_b64 s[84:85], -1
	s_cbranch_vccnz .LBB0_2030
	s_mov_b64 s[88:89], -1
	s_mov_b64 s[84:85], 0
	s_cmp_lt_i32 s80, 7
	s_mov_b64 s[86:87], 0
	s_cbranch_scc1 .LBB0_2033
	s_cmp_eq_u32 s80, 7
	s_mov_b64 s[86:87], -1
	s_cbranch_scc0 .LBB0_2027
	v_mov_b32_e32 v130, v171
	v_cvt_pk_fp8_f32 v130, v124, v125
	v_mov_b32_e32 v131, v171
	v_cvt_pk_fp8_f32 v131, v120, v121
	s_add_i32 s60, s58, s33
	v_cvt_pk_fp8_f32 v130, v126, v127 op_sel:[0,0,1]
	s_ashr_i32 s61, s60, 31
	v_cvt_pk_fp8_f32 v131, v122, v123 op_sel:[0,0,1]
	s_lshl_b64 s[60:61], s[60:61], 12
	v_lshl_add_u64 v[128:129], v[182:183], 0, s[60:61]
	v_lshrrev_b32_e32 v252, 2, v128
	v_lshlrev_b32_e32 v253, 4, v128
	v_and_b32_e32 v252, 0xf0, v252
	v_and_b32_e32 v253, 0x300, v253
	v_and_b32_e32 v128, 0xfffffc0f, v128
	v_or3_b32 v128, v128, v252, v253
	v_lshrrev_b32_e32 v132, 8, v130
	global_store_byte v[128:129], v130, off
	global_store_byte v[128:129], v132, off offset:16
	global_store_byte_d16_hi v[128:129], v130, off offset:32
	v_lshrrev_b32_e32 v130, 24, v130
	global_store_byte v[128:129], v130, off offset:48
	global_store_byte v[128:129], v131, off offset:64
	v_lshrrev_b32_e32 v130, 8, v131
	global_store_byte v[128:129], v130, off offset:80
	global_store_byte_d16_hi v[128:129], v131, off offset:96
	v_lshrrev_b32_e32 v130, 24, v131
	global_store_byte v[128:129], v130, off offset:112
	s_mov_b64 s[86:87], 0

.LBB0_2036:
	v_mov_b32_e32 v130, v171
	v_mov_b32_e32 v131, v171
	v_cvt_pk_fp8_f32 v130, v124, v125
	v_cvt_pk_fp8_f32 v131, v120, v121
	v_lshlrev_b64 v[128:129], 6, v[128:129]
	v_lshl_add_u64 v[128:129], v[184:185], 0, v[128:129]
	v_cvt_pk_fp8_f32 v130, v126, v127 op_sel:[0,0,1]
	v_cvt_pk_fp8_f32 v131, v122, v123 op_sel:[0,0,1]
	v_lshrrev_b32_e32 v252, 2, v128
	v_lshlrev_b32_e32 v253, 4, v128
	v_and_b32_e32 v252, 0xf0, v252
	v_and_b32_e32 v253, 0x300, v253
	v_and_b32_e32 v128, 0xfffffc0f, v128
	v_or3_b32 v128, v128, v252, v253
	global_store_dwordx2 v[128:129], v[130:131], off sc1

.LBB0_2048:
	s_waitcnt lgkmcnt(6)
	v_mov_b32_e32 v140, v202
	s_waitcnt lgkmcnt(4)
	v_mov_b32_e32 v141, v202
	v_pk_mul_f32 v[138:139], v[140:141], v[138:139]
	v_pk_mul_f32 v[136:137], v[202:203], v[136:137]
	v_pk_mul_f32 v[140:141], v[140:141], v[146:147]
	v_pk_mul_f32 v[142:143], v[202:203], v[144:145]
	s_and_b64 vcc, exec, s[12:13]
	s_mov_b64 s[84:85], -1
	s_cbranch_vccnz .LBB0_2060
	s_mov_b64 s[88:89], -1
	s_mov_b64 s[84:85], 0
	s_cmp_lt_i32 s80, 7
	s_mov_b64 s[86:87], 0
	s_cbranch_scc1 .LBB0_2055
	s_cmp_eq_u32 s80, 7
	s_mov_b64 s[86:87], -1
	s_cbranch_scc0 .LBB0_2052
	v_mov_b32_e32 v146, v171
	v_cvt_pk_fp8_f32 v146, v136, v137
	v_mov_b32_e32 v147, v171
	v_cvt_pk_fp8_f32 v147, v142, v143
	s_add_i32 s60, s58, s30
	v_cvt_pk_fp8_f32 v146, v138, v139 op_sel:[0,0,1]
	s_ashr_i32 s61, s60, 31
	v_cvt_pk_fp8_f32 v147, v140, v141 op_sel:[0,0,1]
	s_lshl_b64 s[60:61], s[60:61], 12
	v_lshl_add_u64 v[144:145], v[178:179], 0, s[60:61]
	v_lshrrev_b32_e32 v252, 2, v144
	v_lshlrev_b32_e32 v253, 4, v144
	v_and_b32_e32 v252, 0xf0, v252
	v_and_b32_e32 v253, 0x300, v253
	v_and_b32_e32 v144, 0xfffffc0f, v144
	v_or3_b32 v144, v144, v252, v253
	v_lshrrev_b32_e32 v148, 8, v146
	global_store_byte v[144:145], v146, off offset:4
	global_store_byte v[144:145], v148, off offset:20
	global_store_byte_d16_hi v[144:145], v146, off offset:36
	v_lshrrev_b32_e32 v146, 24, v146
	global_store_byte v[144:145], v146, off offset:52
	global_store_byte v[144:145], v147, off offset:68
	v_lshrrev_b32_e32 v146, 8, v147
	global_store_byte v[144:145], v146, off offset:84
	global_store_byte_d16_hi v[144:145], v147, off offset:100
	v_lshrrev_b32_e32 v146, 24, v147
	global_store_byte v[144:145], v146, off offset:116
	s_mov_b64 s[86:87], 0

.LBB0_2058:
	v_mov_b32_e32 v146, v171
	v_mov_b32_e32 v147, v171
	v_cvt_pk_fp8_f32 v146, v136, v137
	v_cvt_pk_fp8_f32 v147, v142, v143
	v_lshlrev_b64 v[144:145], 6, v[144:145]
	v_lshl_add_u64 v[144:145], v[180:181], 0, v[144:145]
	v_cvt_pk_fp8_f32 v146, v138, v139 op_sel:[0,0,1]
	v_cvt_pk_fp8_f32 v147, v140, v141 op_sel:[0,0,1]
	v_lshrrev_b32_e32 v252, 2, v144
	v_lshlrev_b32_e32 v253, 4, v144
	v_and_b32_e32 v252, 0xf0, v252
	v_and_b32_e32 v253, 0x300, v253
	v_and_b32_e32 v144, 0xfffffc0f, v144
	v_or3_b32 v144, v144, v252, v253
	global_store_dwordx2 v[144:145], v[146:147], off sc1

.LBB0_2070:
	s_waitcnt vmcnt(3)
	v_mov_b32_e32 v120, v202
	v_mov_b32_e32 v121, v202
	v_pk_mul_f32 v[118:119], v[120:121], v[118:119]
	v_pk_mul_f32 v[116:117], v[202:203], v[116:117]
	v_pk_mul_f32 v[114:115], v[120:121], v[114:115]
	v_pk_mul_f32 v[112:113], v[202:203], v[112:113]
	s_and_b64 vcc, exec, s[12:13]
	s_mov_b64 s[84:85], -1
	s_cbranch_vccnz .LBB0_2077
	s_mov_b64 s[88:89], -1
	s_mov_b64 s[84:85], 0
	s_cmp_lt_i32 s80, 7
	s_mov_b64 s[86:87], 0
	s_cbranch_scc1 .LBB0_2080
	s_cmp_eq_u32 s80, 7
	s_mov_b64 s[86:87], -1
	s_cbranch_scc0 .LBB0_2074
	v_mov_b32_e32 v122, v171
	v_cvt_pk_fp8_f32 v122, v116, v117
	v_mov_b32_e32 v123, v171
	v_cvt_pk_fp8_f32 v123, v112, v113
	s_add_i32 s60, s58, s33
	v_cvt_pk_fp8_f32 v122, v118, v119 op_sel:[0,0,1]
	s_ashr_i32 s61, s60, 31
	v_cvt_pk_fp8_f32 v123, v114, v115 op_sel:[0,0,1]
	s_lshl_b64 s[60:61], s[60:61], 12
	v_lshl_add_u64 v[120:121], v[182:183], 0, s[60:61]
	v_lshrrev_b32_e32 v252, 2, v120
	v_lshlrev_b32_e32 v253, 4, v120
	v_and_b32_e32 v252, 0xf0, v252
	v_and_b32_e32 v253, 0x300, v253
	v_and_b32_e32 v120, 0xfffffc0f, v120
	v_or3_b32 v120, v120, v252, v253
	s_waitcnt vmcnt(1)
	v_lshrrev_b32_e32 v124, 8, v122
	global_store_byte v[120:121], v122, off offset:4
	global_store_byte v[120:121], v124, off offset:20
	global_store_byte_d16_hi v[120:121], v122, off offset:36
	v_lshrrev_b32_e32 v122, 24, v122
	global_store_byte v[120:121], v122, off offset:52
	global_store_byte v[120:121], v123, off offset:68
	v_lshrrev_b32_e32 v122, 8, v123
	global_store_byte v[120:121], v122, off offset:84
	global_store_byte_d16_hi v[120:121], v123, off offset:100
	v_lshrrev_b32_e32 v122, 24, v123
	global_store_byte v[120:121], v122, off offset:116
	s_mov_b64 s[86:87], 0

.LBB0_2083:
	v_mov_b32_e32 v122, v171
	v_mov_b32_e32 v123, v171
	v_cvt_pk_fp8_f32 v122, v116, v117
	v_cvt_pk_fp8_f32 v123, v112, v113
	v_lshlrev_b64 v[120:121], 6, v[120:121]
	v_lshl_add_u64 v[120:121], v[184:185], 0, v[120:121]
	v_cvt_pk_fp8_f32 v122, v118, v119 op_sel:[0,0,1]
	v_cvt_pk_fp8_f32 v123, v114, v115 op_sel:[0,0,1]
	v_lshrrev_b32_e32 v252, 2, v120
	v_lshlrev_b32_e32 v253, 4, v120
	v_and_b32_e32 v252, 0xf0, v252
	v_and_b32_e32 v253, 0x300, v253
	v_and_b32_e32 v120, 0xfffffc0f, v120
	v_or3_b32 v120, v120, v252, v253
	global_store_dwordx2 v[120:121], v[122:123], off sc1

.LBB0_2095:
	s_waitcnt vmcnt(0) lgkmcnt(6)
	v_mov_b32_e32 v132, v202
	s_waitcnt lgkmcnt(4)
	v_mov_b32_e32 v133, v202
	v_pk_mul_f32 v[130:131], v[132:133], v[130:131]
	v_pk_mul_f32 v[128:129], v[202:203], v[128:129]
	v_pk_mul_f32 v[132:133], v[132:133], v[138:139]
	v_pk_mul_f32 v[134:135], v[202:203], v[136:137]
	s_and_b64 vcc, exec, s[12:13]
	s_mov_b64 s[84:85], -1
	s_cbranch_vccnz .LBB0_2107
	s_mov_b64 s[88:89], -1
	s_mov_b64 s[84:85], 0
	s_cmp_lt_i32 s80, 7
	s_mov_b64 s[86:87], 0
	s_cbranch_scc1 .LBB0_2102
	s_cmp_eq_u32 s80, 7
	s_mov_b64 s[86:87], -1
	s_cbranch_scc0 .LBB0_2099
	v_mov_b32_e32 v138, v171
	v_cvt_pk_fp8_f32 v138, v128, v129
	v_mov_b32_e32 v139, v171
	v_cvt_pk_fp8_f32 v139, v134, v135
	s_add_i32 s60, s58, s30
	v_cvt_pk_fp8_f32 v138, v130, v131 op_sel:[0,0,1]
	s_ashr_i32 s61, s60, 31
	v_cvt_pk_fp8_f32 v139, v132, v133 op_sel:[0,0,1]
	s_lshl_b64 s[60:61], s[60:61], 12
	v_lshl_add_u64 v[136:137], v[178:179], 0, s[60:61]
	v_lshrrev_b32_e32 v252, 2, v136
	v_lshlrev_b32_e32 v253, 4, v136
	v_and_b32_e32 v252, 0xf0, v252
	v_and_b32_e32 v253, 0x300, v253
	v_and_b32_e32 v136, 0xfffffc0f, v136
	v_or3_b32 v136, v136, v252, v253
	v_lshrrev_b32_e32 v140, 8, v138
	global_store_byte v[136:137], v138, off offset:8
	global_store_byte v[136:137], v140, off offset:24
	global_store_byte_d16_hi v[136:137], v138, off offset:40
	v_lshrrev_b32_e32 v138, 24, v138
	global_store_byte v[136:137], v138, off offset:56
	global_store_byte v[136:137], v139, off offset:72
	v_lshrrev_b32_e32 v138, 8, v139
	global_store_byte v[136:137], v138, off offset:88
	global_store_byte_d16_hi v[136:137], v139, off offset:104
	v_lshrrev_b32_e32 v138, 24, v139
	global_store_byte v[136:137], v138, off offset:120
	s_mov_b64 s[86:87], 0

.LBB0_2105:
	v_mov_b32_e32 v138, v171
	v_mov_b32_e32 v139, v171
	v_cvt_pk_fp8_f32 v138, v128, v129
	v_cvt_pk_fp8_f32 v139, v134, v135
	v_lshlrev_b64 v[136:137], 6, v[136:137]
	v_lshl_add_u64 v[136:137], v[180:181], 0, v[136:137]
	v_cvt_pk_fp8_f32 v138, v130, v131 op_sel:[0,0,1]
	v_cvt_pk_fp8_f32 v139, v132, v133 op_sel:[0,0,1]
	v_lshrrev_b32_e32 v252, 2, v136
	v_lshlrev_b32_e32 v253, 4, v136
	v_and_b32_e32 v252, 0xf0, v252
	v_and_b32_e32 v253, 0x300, v253
	v_and_b32_e32 v136, 0xfffffc0f, v136
	v_or3_b32 v136, v136, v252, v253
	global_store_dwordx2 v[136:137], v[138:139], off sc1

.LBB0_2117:
	v_mov_b32_e32 v112, v202
	v_mov_b32_e32 v113, v202
	v_pk_mul_f32 v[110:111], v[112:113], v[110:111]
	v_pk_mul_f32 v[108:109], v[202:203], v[108:109]
	v_pk_mul_f32 v[106:107], v[112:113], v[106:107]
	v_pk_mul_f32 v[104:105], v[202:203], v[104:105]
	s_and_b64 vcc, exec, s[12:13]
	s_mov_b64 s[84:85], -1
	s_cbranch_vccnz .LBB0_2124
	s_mov_b64 s[88:89], -1
	s_mov_b64 s[84:85], 0
	s_cmp_lt_i32 s80, 7
	s_mov_b64 s[86:87], 0
	s_cbranch_scc1 .LBB0_2127
	s_cmp_eq_u32 s80, 7
	s_mov_b64 s[86:87], -1
	s_cbranch_scc0 .LBB0_2121
	v_mov_b32_e32 v114, v171
	v_cvt_pk_fp8_f32 v114, v108, v109
	v_mov_b32_e32 v115, v171
	v_cvt_pk_fp8_f32 v115, v104, v105
	s_add_i32 s60, s58, s33
	v_cvt_pk_fp8_f32 v114, v110, v111 op_sel:[0,0,1]
	s_ashr_i32 s61, s60, 31
	v_cvt_pk_fp8_f32 v115, v106, v107 op_sel:[0,0,1]
	s_lshl_b64 s[60:61], s[60:61], 12
	v_lshl_add_u64 v[112:113], v[182:183], 0, s[60:61]
	v_lshrrev_b32_e32 v252, 2, v112
	v_lshlrev_b32_e32 v253, 4, v112
	v_and_b32_e32 v252, 0xf0, v252
	v_and_b32_e32 v253, 0x300, v253
	v_and_b32_e32 v112, 0xfffffc0f, v112
	v_or3_b32 v112, v112, v252, v253
	v_lshrrev_b32_e32 v116, 8, v114
	global_store_byte v[112:113], v114, off offset:8
	global_store_byte v[112:113], v116, off offset:24
	global_store_byte_d16_hi v[112:113], v114, off offset:40
	v_lshrrev_b32_e32 v114, 24, v114
	global_store_byte v[112:113], v114, off offset:56
	global_store_byte v[112:113], v115, off offset:72
	v_lshrrev_b32_e32 v114, 8, v115
	global_store_byte v[112:113], v114, off offset:88
	global_store_byte_d16_hi v[112:113], v115, off offset:104
	v_lshrrev_b32_e32 v114, 24, v115
	global_store_byte v[112:113], v114, off offset:120
	s_mov_b64 s[86:87], 0

.LBB0_2130:
	v_mov_b32_e32 v114, v171
	v_mov_b32_e32 v115, v171
	v_cvt_pk_fp8_f32 v114, v108, v109
	v_cvt_pk_fp8_f32 v115, v104, v105
	v_lshlrev_b64 v[112:113], 6, v[112:113]
	v_lshl_add_u64 v[112:113], v[184:185], 0, v[112:113]
	v_cvt_pk_fp8_f32 v114, v110, v111 op_sel:[0,0,1]
	v_cvt_pk_fp8_f32 v115, v106, v107 op_sel:[0,0,1]
	v_lshrrev_b32_e32 v252, 2, v112
	v_lshlrev_b32_e32 v253, 4, v112
	v_and_b32_e32 v252, 0xf0, v252
	v_and_b32_e32 v253, 0x300, v253
	v_and_b32_e32 v112, 0xfffffc0f, v112
	v_or3_b32 v112, v112, v252, v253
	global_store_dwordx2 v[112:113], v[114:115], off sc1

.LBB0_2142:
	s_waitcnt lgkmcnt(6)
	v_mov_b32_e32 v124, v202
	s_waitcnt lgkmcnt(4)
	v_mov_b32_e32 v125, v202
	v_pk_mul_f32 v[122:123], v[124:125], v[122:123]
	v_pk_mul_f32 v[120:121], v[202:203], v[120:121]
	v_pk_mul_f32 v[124:125], v[124:125], v[130:131]
	v_pk_mul_f32 v[126:127], v[202:203], v[128:129]
	s_and_b64 vcc, exec, s[12:13]
	s_mov_b64 s[84:85], -1
	s_cbranch_vccnz .LBB0_2154
	s_mov_b64 s[88:89], -1
	s_mov_b64 s[84:85], 0
	s_cmp_lt_i32 s80, 7
	s_mov_b64 s[86:87], 0
	s_cbranch_scc1 .LBB0_2149
	s_cmp_eq_u32 s80, 7
	s_mov_b64 s[86:87], -1
	s_cbranch_scc0 .LBB0_2146
	v_mov_b32_e32 v130, v171
	v_cvt_pk_fp8_f32 v130, v120, v121
	v_mov_b32_e32 v131, v171
	v_cvt_pk_fp8_f32 v131, v126, v127
	s_add_i32 s60, s58, s30
	v_cvt_pk_fp8_f32 v130, v122, v123 op_sel:[0,0,1]
	s_ashr_i32 s61, s60, 31
	v_cvt_pk_fp8_f32 v131, v124, v125 op_sel:[0,0,1]
	s_lshl_b64 s[60:61], s[60:61], 12
	v_lshl_add_u64 v[128:129], v[186:187], 0, s[60:61]
	v_lshrrev_b32_e32 v252, 2, v128
	v_lshlrev_b32_e32 v253, 4, v128
	v_and_b32_e32 v252, 0xf0, v252
	v_and_b32_e32 v253, 0x300, v253
	v_and_b32_e32 v128, 0xfffffc0f, v128
	v_or3_b32 v128, v128, v252, v253
	v_lshrrev_b32_e32 v132, 8, v130
	global_store_byte v[128:129], v130, off
	global_store_byte v[128:129], v132, off offset:16
	global_store_byte_d16_hi v[128:129], v130, off offset:32
	v_lshrrev_b32_e32 v130, 24, v130
	global_store_byte v[128:129], v130, off offset:48
	global_store_byte v[128:129], v131, off offset:64
	v_lshrrev_b32_e32 v130, 8, v131
	global_store_byte v[128:129], v130, off offset:80
	global_store_byte_d16_hi v[128:129], v131, off offset:96
	v_lshrrev_b32_e32 v130, 24, v131
	global_store_byte v[128:129], v130, off offset:112
	s_mov_b64 s[86:87], 0

.LBB0_2152:
	v_mov_b32_e32 v130, v171
	v_mov_b32_e32 v131, v171
	v_cvt_pk_fp8_f32 v130, v120, v121
	v_cvt_pk_fp8_f32 v131, v126, v127
	v_lshlrev_b64 v[128:129], 6, v[128:129]
	v_lshl_add_u64 v[128:129], v[180:181], 0, v[128:129]
	v_cvt_pk_fp8_f32 v130, v122, v123 op_sel:[0,0,1]
	v_cvt_pk_fp8_f32 v131, v124, v125 op_sel:[0,0,1]
	v_lshrrev_b32_e32 v252, 2, v128
	v_lshlrev_b32_e32 v253, 4, v128
	v_and_b32_e32 v252, 0xf0, v252
	v_and_b32_e32 v253, 0x300, v253
	v_and_b32_e32 v128, 0xfffffc0f, v128
	v_or3_b32 v128, v128, v252, v253
	global_store_dwordx2 v[128:129], v[130:131], off sc1

.LBB0_2164:
	s_waitcnt vmcnt(3)
	v_mov_b32_e32 v104, v202
	v_mov_b32_e32 v105, v202
	v_pk_mul_f32 v[102:103], v[104:105], v[102:103]
	v_pk_mul_f32 v[100:101], v[202:203], v[100:101]
	v_pk_mul_f32 v[98:99], v[104:105], v[98:99]
	v_pk_mul_f32 v[96:97], v[202:203], v[96:97]
	s_and_b64 vcc, exec, s[12:13]
	s_mov_b64 s[84:85], -1
	s_cbranch_vccnz .LBB0_2171
	s_mov_b64 s[88:89], -1
	s_mov_b64 s[84:85], 0
	s_cmp_lt_i32 s80, 7
	s_mov_b64 s[86:87], 0
	s_cbranch_scc1 .LBB0_2174
	s_cmp_eq_u32 s80, 7
	s_mov_b64 s[86:87], -1
	s_cbranch_scc0 .LBB0_2168
	v_mov_b32_e32 v106, v171
	v_cvt_pk_fp8_f32 v106, v100, v101
	v_mov_b32_e32 v107, v171
	v_cvt_pk_fp8_f32 v107, v96, v97
	s_add_i32 s58, s58, s33
	v_cvt_pk_fp8_f32 v106, v102, v103 op_sel:[0,0,1]
	s_ashr_i32 s59, s58, 31
	v_cvt_pk_fp8_f32 v107, v98, v99 op_sel:[0,0,1]
	s_lshl_b64 s[58:59], s[58:59], 12
	v_lshl_add_u64 v[104:105], v[188:189], 0, s[58:59]
	v_lshrrev_b32_e32 v252, 2, v104
	v_lshlrev_b32_e32 v253, 4, v104
	v_and_b32_e32 v252, 0xf0, v252
	v_and_b32_e32 v253, 0x300, v253
	v_and_b32_e32 v104, 0xfffffc0f, v104
	v_or3_b32 v104, v104, v252, v253
	s_waitcnt vmcnt(1)
	v_lshrrev_b32_e32 v108, 8, v106
	global_store_byte v[104:105], v106, off
	global_store_byte v[104:105], v108, off offset:16
	global_store_byte_d16_hi v[104:105], v106, off offset:32
	v_lshrrev_b32_e32 v106, 24, v106
	global_store_byte v[104:105], v106, off offset:48
	global_store_byte v[104:105], v107, off offset:64
	v_lshrrev_b32_e32 v106, 8, v107
	global_store_byte v[104:105], v106, off offset:80
	global_store_byte_d16_hi v[104:105], v107, off offset:96
	v_lshrrev_b32_e32 v106, 24, v107
	global_store_byte v[104:105], v106, off offset:112
	s_mov_b64 s[86:87], 0

.LBB0_2177:
	v_mov_b32_e32 v106, v171
	v_mov_b32_e32 v107, v171
	v_cvt_pk_fp8_f32 v106, v100, v101
	v_cvt_pk_fp8_f32 v107, v96, v97
	v_lshlrev_b64 v[104:105], 6, v[104:105]
	v_lshl_add_u64 v[104:105], v[184:185], 0, v[104:105]
	v_cvt_pk_fp8_f32 v106, v102, v103 op_sel:[0,0,1]
	v_cvt_pk_fp8_f32 v107, v98, v99 op_sel:[0,0,1]
	v_lshrrev_b32_e32 v252, 2, v104
	v_lshlrev_b32_e32 v253, 4, v104
	v_and_b32_e32 v252, 0xf0, v252
	v_and_b32_e32 v253, 0x300, v253
	v_and_b32_e32 v104, 0xfffffc0f, v104
	v_or3_b32 v104, v104, v252, v253
	global_store_dwordx2 v[104:105], v[106:107], off sc1

.LBB0_2189:
	s_waitcnt vmcnt(0) lgkmcnt(6)
	v_mov_b32_e32 v116, v202
	s_waitcnt lgkmcnt(4)
	v_mov_b32_e32 v117, v202
	v_ashrrev_i32_e32 v136, 6, v128
	v_pk_mul_f32 v[114:115], v[116:117], v[114:115]
	v_pk_mul_f32 v[112:113], v[202:203], v[112:113]
	v_pk_mul_f32 v[116:117], v[116:117], v[122:123]
	v_pk_mul_f32 v[118:119], v[202:203], v[120:121]
	s_and_b64 vcc, exec, s[12:13]
	s_mov_b64 s[84:85], -1
	s_cbranch_vccnz .LBB0_2201
	s_mov_b64 s[88:89], -1
	s_mov_b64 s[84:85], 0
	s_cmp_lt_i32 s80, 7
	s_mov_b64 s[86:87], 0
	s_cbranch_scc1 .LBB0_2196
	s_cmp_eq_u32 s80, 7
	s_mov_b64 s[86:87], -1
	s_cbranch_scc0 .LBB0_2193
	v_mov_b32_e32 v122, v171
	v_cvt_pk_fp8_f32 v122, v112, v113
	v_mov_b32_e32 v123, v171
	v_cvt_pk_fp8_f32 v123, v118, v119
	v_add_u32_e32 v120, s30, v136
	v_cvt_pk_fp8_f32 v122, v114, v115 op_sel:[0,0,1]
	v_ashrrev_i32_e32 v121, 31, v120
	v_cvt_pk_fp8_f32 v123, v116, v117 op_sel:[0,0,1]
	v_lshlrev_b64 v[120:121], 12, v[120:121]
	v_lshl_add_u64 v[120:121], v[178:179], 0, v[120:121]
	v_lshrrev_b32_e32 v252, 2, v120
	v_lshlrev_b32_e32 v253, 4, v120
	v_and_b32_e32 v252, 0xf0, v252
	v_and_b32_e32 v253, 0x300, v253
	v_and_b32_e32 v120, 0xfffffc0f, v120
	v_or3_b32 v120, v120, v252, v253
	v_lshrrev_b32_e32 v124, 8, v122
	global_store_byte v[120:121], v122, off
	global_store_byte v[120:121], v124, off offset:16
	global_store_byte_d16_hi v[120:121], v122, off offset:32
	v_lshrrev_b32_e32 v122, 24, v122
	global_store_byte v[120:121], v122, off offset:48
	global_store_byte v[120:121], v123, off offset:64
	v_lshrrev_b32_e32 v122, 8, v123
	global_store_byte v[120:121], v122, off offset:80
	global_store_byte_d16_hi v[120:121], v123, off offset:96
	v_lshrrev_b32_e32 v122, 24, v123
	global_store_byte v[120:121], v122, off offset:112
	s_mov_b64 s[86:87], 0

.LBB0_2199:
	v_mov_b32_e32 v122, v171
	v_mov_b32_e32 v123, v171
	v_cvt_pk_fp8_f32 v122, v112, v113
	v_cvt_pk_fp8_f32 v123, v118, v119
	v_lshlrev_b64 v[120:121], 6, v[120:121]
	v_lshl_add_u64 v[120:121], v[180:181], 0, v[120:121]
	v_cvt_pk_fp8_f32 v122, v114, v115 op_sel:[0,0,1]
	v_cvt_pk_fp8_f32 v123, v116, v117 op_sel:[0,0,1]
	v_lshrrev_b32_e32 v252, 2, v120
	v_lshlrev_b32_e32 v253, 4, v120
	v_and_b32_e32 v252, 0xf0, v252
	v_and_b32_e32 v253, 0x300, v253
	v_and_b32_e32 v120, 0xfffffc0f, v120
	v_or3_b32 v120, v120, v252, v253
	global_store_dwordx2 v[120:121], v[122:123], off sc1

.LBB0_2211:
	v_mov_b32_e32 v96, v202
	v_mov_b32_e32 v97, v202
	v_pk_mul_f32 v[94:95], v[96:97], v[94:95]
	v_pk_mul_f32 v[92:93], v[202:203], v[92:93]
	v_pk_mul_f32 v[90:91], v[96:97], v[90:91]
	v_pk_mul_f32 v[88:89], v[202:203], v[88:89]
	s_and_b64 vcc, exec, s[12:13]
	s_mov_b64 s[84:85], -1
	s_cbranch_vccnz .LBB0_2218
	s_mov_b64 s[88:89], -1
	s_mov_b64 s[84:85], 0
	s_cmp_lt_i32 s80, 7
	s_mov_b64 s[86:87], 0
	s_cbranch_scc1 .LBB0_2221
	s_cmp_eq_u32 s80, 7
	s_mov_b64 s[86:87], -1
	s_cbranch_scc0 .LBB0_2215
	v_mov_b32_e32 v98, v171
	v_cvt_pk_fp8_f32 v98, v92, v93
	v_mov_b32_e32 v99, v171
	v_cvt_pk_fp8_f32 v99, v88, v89
	v_add_u32_e32 v96, s33, v136
	v_cvt_pk_fp8_f32 v98, v94, v95 op_sel:[0,0,1]
	v_ashrrev_i32_e32 v97, 31, v96
	v_cvt_pk_fp8_f32 v99, v90, v91 op_sel:[0,0,1]
	v_lshlrev_b64 v[96:97], 12, v[96:97]
	v_lshl_add_u64 v[96:97], v[182:183], 0, v[96:97]
	v_lshrrev_b32_e32 v252, 2, v96
	v_lshlrev_b32_e32 v253, 4, v96
	v_and_b32_e32 v252, 0xf0, v252
	v_and_b32_e32 v253, 0x300, v253
	v_and_b32_e32 v96, 0xfffffc0f, v96
	v_or3_b32 v96, v96, v252, v253
	v_lshrrev_b32_e32 v100, 8, v98
	global_store_byte v[96:97], v98, off
	global_store_byte v[96:97], v100, off offset:16
	global_store_byte_d16_hi v[96:97], v98, off offset:32
	v_lshrrev_b32_e32 v98, 24, v98
	global_store_byte v[96:97], v98, off offset:48
	global_store_byte v[96:97], v99, off offset:64
	v_lshrrev_b32_e32 v98, 8, v99
	global_store_byte v[96:97], v98, off offset:80
	global_store_byte_d16_hi v[96:97], v99, off offset:96
	v_lshrrev_b32_e32 v98, 24, v99
	global_store_byte v[96:97], v98, off offset:112
	s_mov_b64 s[86:87], 0

.LBB0_2224:
	v_mov_b32_e32 v98, v171
	v_mov_b32_e32 v99, v171
	v_cvt_pk_fp8_f32 v98, v92, v93
	v_cvt_pk_fp8_f32 v99, v88, v89
	v_lshlrev_b64 v[96:97], 6, v[96:97]
	v_lshl_add_u64 v[96:97], v[184:185], 0, v[96:97]
	v_cvt_pk_fp8_f32 v98, v94, v95 op_sel:[0,0,1]
	v_cvt_pk_fp8_f32 v99, v90, v91 op_sel:[0,0,1]
	v_lshrrev_b32_e32 v252, 2, v96
	v_lshlrev_b32_e32 v253, 4, v96
	v_and_b32_e32 v252, 0xf0, v252
	v_and_b32_e32 v253, 0x300, v253
	v_and_b32_e32 v96, 0xfffffc0f, v96
	v_or3_b32 v96, v96, v252, v253
	global_store_dwordx2 v[96:97], v[98:99], off sc1

.LBB0_2236:
	s_waitcnt lgkmcnt(6)
	v_mov_b32_e32 v108, v202
	s_waitcnt lgkmcnt(4)
	v_mov_b32_e32 v109, v202
	v_pk_mul_f32 v[106:107], v[108:109], v[106:107]
	v_pk_mul_f32 v[104:105], v[202:203], v[104:105]
	v_pk_mul_f32 v[108:109], v[108:109], v[114:115]
	v_pk_mul_f32 v[110:111], v[202:203], v[112:113]
	s_and_b64 vcc, exec, s[12:13]
	s_mov_b64 s[84:85], -1
	s_cbranch_vccnz .LBB0_2248
	s_mov_b64 s[88:89], -1
	s_mov_b64 s[84:85], 0
	s_cmp_lt_i32 s80, 7
	s_mov_b64 s[86:87], 0
	s_cbranch_scc1 .LBB0_2243
	s_cmp_eq_u32 s80, 7
	s_mov_b64 s[86:87], -1
	s_cbranch_scc0 .LBB0_2240
	v_mov_b32_e32 v114, v171
	v_cvt_pk_fp8_f32 v114, v104, v105
	v_mov_b32_e32 v115, v171
	v_cvt_pk_fp8_f32 v115, v110, v111
	v_add_u32_e32 v112, s30, v136
	v_cvt_pk_fp8_f32 v114, v106, v107 op_sel:[0,0,1]
	v_ashrrev_i32_e32 v113, 31, v112
	v_cvt_pk_fp8_f32 v115, v108, v109 op_sel:[0,0,1]
	v_lshlrev_b64 v[112:113], 12, v[112:113]
	v_lshl_add_u64 v[112:113], v[178:179], 0, v[112:113]
	v_lshrrev_b32_e32 v252, 2, v112
	v_lshlrev_b32_e32 v253, 4, v112
	v_and_b32_e32 v252, 0xf0, v252
	v_and_b32_e32 v253, 0x300, v253
	v_and_b32_e32 v112, 0xfffffc0f, v112
	v_or3_b32 v112, v112, v252, v253
	v_lshrrev_b32_e32 v116, 8, v114
	global_store_byte v[112:113], v114, off offset:4
	global_store_byte v[112:113], v116, off offset:20
	global_store_byte_d16_hi v[112:113], v114, off offset:36
	v_lshrrev_b32_e32 v114, 24, v114
	global_store_byte v[112:113], v114, off offset:52
	global_store_byte v[112:113], v115, off offset:68
	v_lshrrev_b32_e32 v114, 8, v115
	global_store_byte v[112:113], v114, off offset:84
	global_store_byte_d16_hi v[112:113], v115, off offset:100
	v_lshrrev_b32_e32 v114, 24, v115
	global_store_byte v[112:113], v114, off offset:116
	s_mov_b64 s[86:87], 0

.LBB0_2246:
	v_mov_b32_e32 v114, v171
	v_mov_b32_e32 v115, v171
	v_cvt_pk_fp8_f32 v114, v104, v105
	v_cvt_pk_fp8_f32 v115, v110, v111
	v_lshlrev_b64 v[112:113], 6, v[112:113]
	v_lshl_add_u64 v[112:113], v[180:181], 0, v[112:113]
	v_cvt_pk_fp8_f32 v114, v106, v107 op_sel:[0,0,1]
	v_cvt_pk_fp8_f32 v115, v108, v109 op_sel:[0,0,1]
	v_lshrrev_b32_e32 v252, 2, v112
	v_lshlrev_b32_e32 v253, 4, v112
	v_and_b32_e32 v252, 0xf0, v252
	v_and_b32_e32 v253, 0x300, v253
	v_and_b32_e32 v112, 0xfffffc0f, v112
	v_or3_b32 v112, v112, v252, v253
	global_store_dwordx2 v[112:113], v[114:115], off sc1

.LBB0_2258:
	s_waitcnt vmcnt(3)
	v_mov_b32_e32 v88, v202
	v_mov_b32_e32 v89, v202
	v_pk_mul_f32 v[86:87], v[88:89], v[86:87]
	v_pk_mul_f32 v[84:85], v[202:203], v[84:85]
	v_pk_mul_f32 v[82:83], v[88:89], v[82:83]
	v_pk_mul_f32 v[80:81], v[202:203], v[80:81]
	s_and_b64 vcc, exec, s[12:13]
	s_mov_b64 s[84:85], -1
	s_cbranch_vccnz .LBB0_2265
	s_mov_b64 s[88:89], -1
	s_mov_b64 s[84:85], 0
	s_cmp_lt_i32 s80, 7
	s_mov_b64 s[86:87], 0
	s_cbranch_scc1 .LBB0_2268
	s_cmp_eq_u32 s80, 7
	s_mov_b64 s[86:87], -1
	s_cbranch_scc0 .LBB0_2262
	v_mov_b32_e32 v90, v171
	v_cvt_pk_fp8_f32 v90, v84, v85
	v_mov_b32_e32 v91, v171
	v_cvt_pk_fp8_f32 v91, v80, v81
	v_add_u32_e32 v88, s33, v136
	v_cvt_pk_fp8_f32 v90, v86, v87 op_sel:[0,0,1]
	v_ashrrev_i32_e32 v89, 31, v88
	v_cvt_pk_fp8_f32 v91, v82, v83 op_sel:[0,0,1]
	v_lshlrev_b64 v[88:89], 12, v[88:89]
	v_lshl_add_u64 v[88:89], v[182:183], 0, v[88:89]
	v_lshrrev_b32_e32 v252, 2, v88
	v_lshlrev_b32_e32 v253, 4, v88
	v_and_b32_e32 v252, 0xf0, v252
	v_and_b32_e32 v253, 0x300, v253
	v_and_b32_e32 v88, 0xfffffc0f, v88
	v_or3_b32 v88, v88, v252, v253
	s_waitcnt vmcnt(1)
	v_lshrrev_b32_e32 v92, 8, v90
	global_store_byte v[88:89], v90, off offset:4
	global_store_byte v[88:89], v92, off offset:20
	global_store_byte_d16_hi v[88:89], v90, off offset:36
	v_lshrrev_b32_e32 v90, 24, v90
	global_store_byte v[88:89], v90, off offset:52
	global_store_byte v[88:89], v91, off offset:68
	v_lshrrev_b32_e32 v90, 8, v91
	global_store_byte v[88:89], v90, off offset:84
	global_store_byte_d16_hi v[88:89], v91, off offset:100
	v_lshrrev_b32_e32 v90, 24, v91
	global_store_byte v[88:89], v90, off offset:116
	s_mov_b64 s[86:87], 0

.LBB0_2271:
	v_mov_b32_e32 v90, v171
	v_mov_b32_e32 v91, v171
	v_cvt_pk_fp8_f32 v90, v84, v85
	v_cvt_pk_fp8_f32 v91, v80, v81
	v_lshlrev_b64 v[88:89], 6, v[88:89]
	v_lshl_add_u64 v[88:89], v[184:185], 0, v[88:89]
	v_cvt_pk_fp8_f32 v90, v86, v87 op_sel:[0,0,1]
	v_cvt_pk_fp8_f32 v91, v82, v83 op_sel:[0,0,1]
	v_lshrrev_b32_e32 v252, 2, v88
	v_lshlrev_b32_e32 v253, 4, v88
	v_and_b32_e32 v252, 0xf0, v252
	v_and_b32_e32 v253, 0x300, v253
	v_and_b32_e32 v88, 0xfffffc0f, v88
	v_or3_b32 v88, v88, v252, v253
	global_store_dwordx2 v[88:89], v[90:91], off sc1

.LBB0_2283:
	s_waitcnt vmcnt(0) lgkmcnt(6)
	v_mov_b32_e32 v100, v202
	s_waitcnt lgkmcnt(4)
	v_mov_b32_e32 v101, v202
	v_pk_mul_f32 v[98:99], v[100:101], v[98:99]
	v_pk_mul_f32 v[96:97], v[202:203], v[96:97]
	v_pk_mul_f32 v[100:101], v[100:101], v[106:107]
	v_pk_mul_f32 v[102:103], v[202:203], v[104:105]
	s_and_b64 vcc, exec, s[12:13]
	s_mov_b64 s[84:85], -1
	s_cbranch_vccnz .LBB0_2295
	s_mov_b64 s[88:89], -1
	s_mov_b64 s[84:85], 0
	s_cmp_lt_i32 s80, 7
	s_mov_b64 s[86:87], 0
	s_cbranch_scc1 .LBB0_2290
	s_cmp_eq_u32 s80, 7
	s_mov_b64 s[86:87], -1
	s_cbranch_scc0 .LBB0_2287
	v_mov_b32_e32 v106, v171
	v_cvt_pk_fp8_f32 v106, v96, v97
	v_mov_b32_e32 v107, v171
	v_cvt_pk_fp8_f32 v107, v102, v103
	v_add_u32_e32 v104, s30, v136
	v_cvt_pk_fp8_f32 v106, v98, v99 op_sel:[0,0,1]
	v_ashrrev_i32_e32 v105, 31, v104
	v_cvt_pk_fp8_f32 v107, v100, v101 op_sel:[0,0,1]
	v_lshlrev_b64 v[104:105], 12, v[104:105]
	v_lshl_add_u64 v[104:105], v[178:179], 0, v[104:105]
	v_lshrrev_b32_e32 v252, 2, v104
	v_lshlrev_b32_e32 v253, 4, v104
	v_and_b32_e32 v252, 0xf0, v252
	v_and_b32_e32 v253, 0x300, v253
	v_and_b32_e32 v104, 0xfffffc0f, v104
	v_or3_b32 v104, v104, v252, v253
	v_lshrrev_b32_e32 v108, 8, v106
	global_store_byte v[104:105], v106, off offset:8
	global_store_byte v[104:105], v108, off offset:24
	global_store_byte_d16_hi v[104:105], v106, off offset:40
	v_lshrrev_b32_e32 v106, 24, v106
	global_store_byte v[104:105], v106, off offset:56
	global_store_byte v[104:105], v107, off offset:72
	v_lshrrev_b32_e32 v106, 8, v107
	global_store_byte v[104:105], v106, off offset:88
	global_store_byte_d16_hi v[104:105], v107, off offset:104
	v_lshrrev_b32_e32 v106, 24, v107
	global_store_byte v[104:105], v106, off offset:120
	s_mov_b64 s[86:87], 0

.LBB0_2293:
	v_mov_b32_e32 v106, v171
	v_mov_b32_e32 v107, v171
	v_cvt_pk_fp8_f32 v106, v96, v97
	v_cvt_pk_fp8_f32 v107, v102, v103
	v_lshlrev_b64 v[104:105], 6, v[104:105]
	v_lshl_add_u64 v[104:105], v[180:181], 0, v[104:105]
	v_cvt_pk_fp8_f32 v106, v98, v99 op_sel:[0,0,1]
	v_cvt_pk_fp8_f32 v107, v100, v101 op_sel:[0,0,1]
	v_lshrrev_b32_e32 v252, 2, v104
	v_lshlrev_b32_e32 v253, 4, v104
	v_and_b32_e32 v252, 0xf0, v252
	v_and_b32_e32 v253, 0x300, v253
	v_and_b32_e32 v104, 0xfffffc0f, v104
	v_or3_b32 v104, v104, v252, v253
	global_store_dwordx2 v[104:105], v[106:107], off sc1

.LBB0_2305:
	v_mov_b32_e32 v80, v202
	v_mov_b32_e32 v81, v202
	v_pk_mul_f32 v[78:79], v[80:81], v[78:79]
	v_pk_mul_f32 v[76:77], v[202:203], v[76:77]
	v_pk_mul_f32 v[74:75], v[80:81], v[74:75]
	v_pk_mul_f32 v[72:73], v[202:203], v[72:73]
	s_and_b64 vcc, exec, s[12:13]
	s_mov_b64 s[84:85], -1
	s_cbranch_vccnz .LBB0_2312
	s_mov_b64 s[88:89], -1
	s_mov_b64 s[84:85], 0
	s_cmp_lt_i32 s80, 7
	s_mov_b64 s[86:87], 0
	s_cbranch_scc1 .LBB0_2315
	s_cmp_eq_u32 s80, 7
	s_mov_b64 s[86:87], -1
	s_cbranch_scc0 .LBB0_2309
	v_mov_b32_e32 v82, v171
	v_cvt_pk_fp8_f32 v82, v76, v77
	v_mov_b32_e32 v83, v171
	v_cvt_pk_fp8_f32 v83, v72, v73
	v_add_u32_e32 v80, s33, v136
	v_cvt_pk_fp8_f32 v82, v78, v79 op_sel:[0,0,1]
	v_ashrrev_i32_e32 v81, 31, v80
	v_cvt_pk_fp8_f32 v83, v74, v75 op_sel:[0,0,1]
	v_lshlrev_b64 v[80:81], 12, v[80:81]
	v_lshl_add_u64 v[80:81], v[182:183], 0, v[80:81]
	v_lshrrev_b32_e32 v252, 2, v80
	v_lshlrev_b32_e32 v253, 4, v80
	v_and_b32_e32 v252, 0xf0, v252
	v_and_b32_e32 v253, 0x300, v253
	v_and_b32_e32 v80, 0xfffffc0f, v80
	v_or3_b32 v80, v80, v252, v253
	v_lshrrev_b32_e32 v84, 8, v82
	global_store_byte v[80:81], v82, off offset:8
	global_store_byte v[80:81], v84, off offset:24
	global_store_byte_d16_hi v[80:81], v82, off offset:40
	v_lshrrev_b32_e32 v82, 24, v82
	global_store_byte v[80:81], v82, off offset:56
	global_store_byte v[80:81], v83, off offset:72
	v_lshrrev_b32_e32 v82, 8, v83
	global_store_byte v[80:81], v82, off offset:88
	global_store_byte_d16_hi v[80:81], v83, off offset:104
	v_lshrrev_b32_e32 v82, 24, v83
	global_store_byte v[80:81], v82, off offset:120
	s_mov_b64 s[86:87], 0

.LBB0_2318:
	v_mov_b32_e32 v82, v171
	v_mov_b32_e32 v83, v171
	v_cvt_pk_fp8_f32 v82, v76, v77
	v_cvt_pk_fp8_f32 v83, v72, v73
	v_lshlrev_b64 v[80:81], 6, v[80:81]
	v_lshl_add_u64 v[80:81], v[184:185], 0, v[80:81]
	v_cvt_pk_fp8_f32 v82, v78, v79 op_sel:[0,0,1]
	v_cvt_pk_fp8_f32 v83, v74, v75 op_sel:[0,0,1]
	v_lshrrev_b32_e32 v252, 2, v80
	v_lshlrev_b32_e32 v253, 4, v80
	v_and_b32_e32 v252, 0xf0, v252
	v_and_b32_e32 v253, 0x300, v253
	v_and_b32_e32 v80, 0xfffffc0f, v80
	v_or3_b32 v80, v80, v252, v253
	global_store_dwordx2 v[80:81], v[82:83], off sc1

.LBB0_2330:
	s_waitcnt lgkmcnt(6)
	v_mov_b32_e32 v92, v202
	s_waitcnt lgkmcnt(4)
	v_mov_b32_e32 v93, v202
	v_pk_mul_f32 v[90:91], v[92:93], v[90:91]
	v_pk_mul_f32 v[88:89], v[202:203], v[88:89]
	v_pk_mul_f32 v[92:93], v[92:93], v[98:99]
	v_pk_mul_f32 v[94:95], v[202:203], v[96:97]
	s_and_b64 vcc, exec, s[12:13]
	s_mov_b64 s[84:85], -1
	s_cbranch_vccnz .LBB0_2342
	s_mov_b64 s[88:89], -1
	s_mov_b64 s[84:85], 0
	s_cmp_lt_i32 s80, 7
	s_mov_b64 s[86:87], 0
	s_cbranch_scc1 .LBB0_2337
	s_cmp_eq_u32 s80, 7
	s_mov_b64 s[86:87], -1
	s_cbranch_scc0 .LBB0_2334
	v_mov_b32_e32 v98, v171
	v_cvt_pk_fp8_f32 v98, v88, v89
	v_mov_b32_e32 v99, v171
	v_cvt_pk_fp8_f32 v99, v94, v95
	v_add_u32_e32 v96, s30, v136
	v_cvt_pk_fp8_f32 v98, v90, v91 op_sel:[0,0,1]
	v_ashrrev_i32_e32 v97, 31, v96
	v_cvt_pk_fp8_f32 v99, v92, v93 op_sel:[0,0,1]
	v_lshlrev_b64 v[96:97], 12, v[96:97]
	v_lshl_add_u64 v[96:97], v[186:187], 0, v[96:97]
	v_lshrrev_b32_e32 v252, 2, v96
	v_lshlrev_b32_e32 v253, 4, v96
	v_and_b32_e32 v252, 0xf0, v252
	v_and_b32_e32 v253, 0x300, v253
	v_and_b32_e32 v96, 0xfffffc0f, v96
	v_or3_b32 v96, v96, v252, v253
	v_lshrrev_b32_e32 v100, 8, v98
	global_store_byte v[96:97], v98, off
	global_store_byte v[96:97], v100, off offset:16
	global_store_byte_d16_hi v[96:97], v98, off offset:32
	v_lshrrev_b32_e32 v98, 24, v98
	global_store_byte v[96:97], v98, off offset:48
	global_store_byte v[96:97], v99, off offset:64
	v_lshrrev_b32_e32 v98, 8, v99
	global_store_byte v[96:97], v98, off offset:80
	global_store_byte_d16_hi v[96:97], v99, off offset:96
	v_lshrrev_b32_e32 v98, 24, v99
	global_store_byte v[96:97], v98, off offset:112
	s_mov_b64 s[86:87], 0

.LBB0_2340:
	v_mov_b32_e32 v98, v171
	v_mov_b32_e32 v99, v171
	v_cvt_pk_fp8_f32 v98, v88, v89
	v_cvt_pk_fp8_f32 v99, v94, v95
	v_lshlrev_b64 v[96:97], 6, v[96:97]
	v_lshl_add_u64 v[96:97], v[180:181], 0, v[96:97]
	v_cvt_pk_fp8_f32 v98, v90, v91 op_sel:[0,0,1]
	v_cvt_pk_fp8_f32 v99, v92, v93 op_sel:[0,0,1]
	v_lshrrev_b32_e32 v252, 2, v96
	v_lshlrev_b32_e32 v253, 4, v96
	v_and_b32_e32 v252, 0xf0, v252
	v_and_b32_e32 v253, 0x300, v253
	v_and_b32_e32 v96, 0xfffffc0f, v96
	v_or3_b32 v96, v96, v252, v253
	global_store_dwordx2 v[96:97], v[98:99], off sc1

.LBB0_2352:
	s_waitcnt vmcnt(3)
	v_mov_b32_e32 v72, v202
	v_mov_b32_e32 v73, v202
	v_pk_mul_f32 v[70:71], v[72:73], v[70:71]
	v_pk_mul_f32 v[68:69], v[202:203], v[68:69]
	v_pk_mul_f32 v[66:67], v[72:73], v[66:67]
	v_pk_mul_f32 v[64:65], v[202:203], v[64:65]
	s_and_b64 vcc, exec, s[12:13]
	s_mov_b64 s[10:11], -1
	s_cbranch_vccnz .LBB0_2364
	s_mov_b64 s[82:83], -1
	s_mov_b64 s[10:11], 0
	s_cmp_lt_i32 s80, 7
	s_mov_b64 s[12:13], 0
	s_cbranch_scc1 .LBB0_2359
	s_cmp_eq_u32 s80, 7
	s_mov_b64 s[12:13], -1
	s_cbranch_scc0 .LBB0_2356
	v_mov_b32_e32 v74, v171
	v_cvt_pk_fp8_f32 v74, v68, v69
	v_mov_b32_e32 v75, v171
	v_cvt_pk_fp8_f32 v75, v64, v65
	v_add_u32_e32 v72, s33, v136
	v_cvt_pk_fp8_f32 v74, v70, v71 op_sel:[0,0,1]
	v_ashrrev_i32_e32 v73, 31, v72
	v_cvt_pk_fp8_f32 v75, v66, v67 op_sel:[0,0,1]
	v_lshlrev_b64 v[72:73], 12, v[72:73]
	v_lshl_add_u64 v[72:73], v[188:189], 0, v[72:73]
	v_lshrrev_b32_e32 v252, 2, v72
	v_lshlrev_b32_e32 v253, 4, v72
	v_and_b32_e32 v252, 0xf0, v252
	v_and_b32_e32 v253, 0x300, v253
	v_and_b32_e32 v72, 0xfffffc0f, v72
	v_or3_b32 v72, v72, v252, v253
	s_waitcnt vmcnt(1)
	v_lshrrev_b32_e32 v76, 8, v74
	global_store_byte v[72:73], v74, off
	global_store_byte v[72:73], v76, off offset:16
	global_store_byte_d16_hi v[72:73], v74, off offset:32
	v_lshrrev_b32_e32 v74, 24, v74
	global_store_byte v[72:73], v74, off offset:48
	global_store_byte v[72:73], v75, off offset:64
	v_lshrrev_b32_e32 v74, 8, v75
	global_store_byte v[72:73], v74, off offset:80
	global_store_byte_d16_hi v[72:73], v75, off offset:96
	v_lshrrev_b32_e32 v74, 24, v75
	global_store_byte v[72:73], v74, off offset:112
	s_mov_b64 s[12:13], 0

.LBB0_2362:
	v_mov_b32_e32 v74, v171
	v_mov_b32_e32 v75, v171
	v_cvt_pk_fp8_f32 v74, v68, v69
	v_cvt_pk_fp8_f32 v75, v64, v65
	v_lshlrev_b64 v[72:73], 6, v[72:73]
	v_lshl_add_u64 v[72:73], v[184:185], 0, v[72:73]
	v_cvt_pk_fp8_f32 v74, v70, v71 op_sel:[0,0,1]
	v_cvt_pk_fp8_f32 v75, v66, v67 op_sel:[0,0,1]
	v_lshrrev_b32_e32 v252, 2, v72
	v_lshlrev_b32_e32 v253, 4, v72
	v_and_b32_e32 v252, 0xf0, v252
	v_and_b32_e32 v253, 0x300, v253
	v_and_b32_e32 v72, 0xfffffc0f, v72
	v_or3_b32 v72, v72, v252, v253
	global_store_dwordx2 v[72:73], v[74:75], off sc1

.LBB0_3923:
	s_lshl_b64 s[14:15], 1, s10
	s_or_b64 s[14:15], s[14:15], s[12:13]
	v_cmp_le_u64_e32 vcc, s[14:15], v[14:15]
	s_bcnt1_i32_b64 s16, vcc
	v_cmp_le_u64_e32 vcc, s[14:15], v[12:13]
	s_bcnt1_i32_b64 s17, vcc
	v_cmp_le_u64_e32 vcc, s[14:15], v[6:7]
	s_add_i32 s16, s17, s16
	s_bcnt1_i32_b64 s17, vcc
	v_cmp_le_u64_e32 vcc, s[14:15], v[4:5]
	s_add_i32 s16, s16, s17
	s_bcnt1_i32_b64 s17, vcc
	s_add_i32 s16, s16, s17
	s_cmp_gt_u32 s16, 15
	s_cselect_b32 s13, s15, s13
	s_cselect_b32 s12, s14, s12
	s_cmp_lg_u32 s16, 16
	s_cselect_b64 s[14:15], -1, 0
	s_cmp_lg_u32 s10, 0
	s_cselect_b64 s[16:17], -1, 0
	s_and_b64 s[14:15], s[14:15], s[16:17]
	s_add_u32 s10, s10, -1
	s_addc_u32 s11, s11, -1
	s_and_b64 vcc, exec, s[14:15]
	s_cbranch_vccnz .LBB0_3923
	v_cmp_le_u64_e32 vcc, s[12:13], v[14:15]
	s_nop 1
	v_and_b32_e32 v9, vcc_lo, v2
	v_and_b32_e32 v8, vcc_hi, v1
	v_bcnt_u32_b32 v9, v9, 0
	v_bcnt_u32_b32 v8, v8, v9
	v_mov_b32_e32 v9, v0
	v_cmp_gt_u64_e64 s[10:11], 16, v[8:9]
	s_and_b64 s[14:15], vcc, s[10:11]
	s_and_saveexec_b64 s[10:11], s[14:15]
	v_lshl_add_u32 v8, v8, 2, s61
	ds_write_b32 v8, v3
	s_or_b64 exec, exec, s[10:11]
	s_bcnt1_i32_b64 s14, vcc
	v_cmp_le_u64_e32 vcc, s[12:13], v[12:13]
	s_nop 1
	v_and_b32_e32 v8, vcc_lo, v2
	v_and_b32_e32 v3, vcc_hi, v1
	v_bcnt_u32_b32 v8, v8, 0
	v_bcnt_u32_b32 v3, v3, v8
	v_add_u32_e32 v3, s14, v3
	v_cmp_gt_u32_e64 s[10:11], 16, v3
	s_and_b64 s[16:17], vcc, s[10:11]
	s_and_saveexec_b64 s[10:11], s[16:17]
	v_lshl_add_u32 v3, v3, 2, s61
	ds_write_b32 v3, v11
	s_or_b64 exec, exec, s[10:11]
	s_bcnt1_i32_b64 s10, vcc
	v_cmp_le_u64_e32 vcc, s[12:13], v[6:7]
	s_add_i32 s14, s10, s14
	s_nop 0
	v_and_b32_e32 v6, vcc_lo, v2
	v_and_b32_e32 v3, vcc_hi, v1
	v_bcnt_u32_b32 v6, v6, 0
	v_bcnt_u32_b32 v3, v3, v6
	v_add_u32_e32 v3, s14, v3
	v_cmp_gt_u32_e64 s[10:11], 16, v3
	s_and_b64 s[16:17], vcc, s[10:11]
	s_and_saveexec_b64 s[10:11], s[16:17]
	v_lshl_add_u32 v3, v3, 2, s61
	ds_write_b32 v3, v20
	s_or_b64 exec, exec, s[10:11]
	s_bcnt1_i32_b64 s10, vcc
	v_cmp_le_u64_e32 vcc, s[12:13], v[4:5]
	s_add_i32 s14, s14, s10
	s_nop 0
	v_and_b32_e32 v2, vcc_lo, v2
	v_and_b32_e32 v1, vcc_hi, v1
	v_bcnt_u32_b32 v2, v2, 0
	v_bcnt_u32_b32 v1, v1, v2
	v_add_u32_e32 v1, s14, v1
	v_cmp_gt_u32_e64 s[10:11], 16, v1
	s_and_b64 s[12:13], vcc, s[10:11]
	s_and_saveexec_b64 s[10:11], s[12:13]
	v_lshl_add_u32 v1, v1, 2, s61
	ds_write_b32 v1, v21
	s_or_b64 exec, exec, s[10:11]
	v_cmp_gt_i32_e32 vcc, s6, v49
	v_mov_b32_e32 v1, s81
	v_mov_b32_e32 v2, s79
	v_cndmask_b32_e32 v3, v1, v2, vcc
	v_mov_b32_e32 v1, s80
	v_mov_b32_e32 v2, s78
	v_cndmask_b32_e32 v2, v1, v2, vcc
	v_and_b32_e32 v4, 0xff0, v124
	v_mov_b32_e32 v5, v0
	v_lshl_add_u64 v[6:7], v[2:3], 0, v[4:5]
	v_cndmask_b32_e64 v1, v174, 0, vcc
	v_mov_b32_e32 v2, s49
	s_movk_i32 s10, 0xfe
	v_add3_u32 v1, s6, v1, v4
	v_sub_u32_e64 v8, s10, v2 clamp
	global_load_dwordx4 v[2:5], v[6:7], off
	s_lshl_b32 s54, s48, 12
	s_mov_b32 s87, s55
	s_lshl_b64 s[12:13], s[86:87], 11
	s_add_u32 s10, s38, s12
	s_addc_u32 s11, s39, s13
	v_lshlrev_b32_e32 v10, 12, v8
	v_mov_b32_e32 v11, v0
	v_lshl_add_u64 v[10:11], v[6:7], 0, v[10:11]
	global_load_dwordx4 v[10:13], v[10:11], off
	v_lshl_add_u64 v[14:15], v[6:7], 0, s[54:55]
	global_load_dwordx4 v[14:17], v[14:15], off
	v_mov_b32_e32 v7, v0
	s_waitcnt vmcnt(2)
	ds_write_b128 v1, v[2:5]
	s_waitcnt vmcnt(1)
	ds_write_b128 v1, v[10:13] offset:8192
	s_waitcnt vmcnt(0)
	ds_write_b128 v1, v[14:17] offset:16384
	v_and_b32_e32 v4, 48, v49
	v_lshlrev_b32_e32 v2, 1, v121
	v_mov_b32_e32 v3, v0
	v_lshl_add_u64 v[2:3], s[10:11], 0, v[2:3]
	v_lshlrev_b32_e32 v6, 1, v4
	v_lshl_add_u64 v[6:7], v[2:3], 0, v[6:7]
	v_mov_b32_e32 v2, v0
	v_mov_b32_e32 v3, v0
	v_mov_b32_e32 v1, v0
	v_mov_b64_e32 v[72:73], v[2:3]
	v_cmp_gt_u32_e64 s[10:11], 4, v122
	v_mov_b64_e32 v[70:71], v[0:1]
	s_waitcnt lgkmcnt(0)
	s_barrier
	v_and_b32_e32 v1, 63, v160
	v_lshrrev_b32_e32 v203, 6, v160
	v_and_b32_e32 v201, 15, v1
	v_lshrrev_b32_e32 v187, 4, v1
	v_readfirstlane_b32 s22, v203
	v_lshrrev_b32_e32 v165, 2, v201
	v_mov_b32_e32 v193, 0
	v_lshlrev_b32_e32 v192, 4, v1
	v_lshl_add_u64 v[166:167], s[78:79], 0, v[192:193]
	v_lshl_add_u64 v[190:191], s[80:81], 0, v[192:193]
	v_add_u32_e32 v188, 0x100, v192
	v_xor_b32_e32 v197, 16, v1
	v_lshlrev_b32_e32 v197, 2, v197
	v_xor_b32_e32 v198, 32, v1
	v_lshlrev_b32_e32 v198, 2, v198
	v_mov_b32_e32 v199, 0xf149f2ca
	v_mov_b32_e32 v200, 0x7149f2ca
	s_lshl_b32 s23, s22, 9
	s_add_i32 s23, s23, 0x20900
	v_lshl_add_u32 v203, v1, 2, s23
	ds_read_b32 v252, v203
	ds_read_b32 v253, v203 offset:256
	s_lshl_b32 s23, s22, 10
	s_add_i32 s23, s23, 0x10900
	v_mov_b32_e32 v244, 0
	v_mov_b32_e32 v245, 0
	v_mov_b32_e32 v246, 0
	v_mov_b32_e32 v247, 0
	v_lshl_add_u32 v133, v1, 4, s23
	ds_write_b128 v133, v[244:247]
	v_lshrrev_b32_e32 v248, 4, v1
	v_lshlrev_b32_e64 v249, v248, 1
	v_lshlrev_b32_e32 v250, 4, v249
	s_waitcnt lgkmcnt(0)
	v_cmp_le_i32_e32 vcc, 0, v252
	v_lshl_add_u32 v203, v252, 2, s23
	s_and_saveexec_b64 s[12:13], vcc
	ds_or_b32 v203, v249
	s_mov_b64 exec, s[12:13]
	v_cmp_le_i32_e32 vcc, 0, v253
	v_lshl_add_u32 v203, v253, 2, s23
	s_and_saveexec_b64 s[12:13], vcc
	ds_or_b32 v203, v250
	s_mov_b64 exec, s[12:13]
	v_lshl_add_u32 v203, v1, 2, s23
	s_waitcnt lgkmcnt(0)
	ds_read_b32 v244, v203
	ds_read_b32 v245, v203 offset:256
	ds_read_b32 v246, v203 offset:512
	ds_read_b32 v247, v203 offset:768
	s_lshl_b32 s23, s22, 12
	s_add_i32 s23, s23, 0x8900
	v_lshl_add_u32 v207, v201, 7, s23
	v_lshl_add_u32 v207, v187, 3, v207
	s_lshl_b32 s21, s22, 3
	s_add_i32 s20, s48, -1
	v_add_u32_e32 v206, s21, v165
	s_lshl_b32 s54, s48, 6
	s_add_i32 s54, s54, s21
	s_and_b32 s101, s65, 3
	s_lshl_b32 s12, s54, 11
	s_lshl_b32 s23, s101, 9
	s_add_i32 s12, s12, s23
	s_add_u32 s12, s38, s12
	s_addc_u32 s13, s39, 0
	v_and_b32_e32 v192, 3, v201
	v_lshlrev_b32_e32 v192, 7, v192
	v_lshl_or_b32 v192, v187, 5, v192
	v_lshl_or_b32 v192, v165, 11, v192
	v_lshl_add_u64 v[192:193], s[12:13], 0, v[192:193]
	global_load_dwordx4 v[212:215], v[192:193], off
	global_load_dwordx4 v[216:219], v[192:193], off offset:16
	v_add_co_u32_e32 v192, vcc, 0x2000, v192
	s_nop 1
	v_addc_co_u32_e32 v193, vcc, 0, v193, vcc
	global_load_dwordx4 v[220:223], v[192:193], off
	global_load_dwordx4 v[224:227], v[192:193], off offset:16
	s_mul_i32 s12, s54, 0xc0
	s_lshl_b32 s23, s101, 4
	s_add_i32 s12, s12, s23
	s_add_i32 s12, s12, 0xf400040
	s_add_u32 s12, s38, s12
	s_addc_u32 s13, s39, 0
	v_and_b32_e32 v133, 3, v201
	v_mul_u32_u24_e32 v248, 0xc0, v165
	v_mov_b32_e32 v249, 0
	v_lshl_add_u32 v248, v133, 2, v248
	v_lshl_add_u64 v[248:249], s[12:13], 0, v[248:249]
	global_load_dword v208, v[248:249], off
	global_load_dword v148, v[248:249], off offset:768
	v_lshlrev_b32_e32 v187, 2, v187
	s_mov_b32 s13, 0
	s_waitcnt lgkmcnt(0)
	v_lshl_or_b32 v164, v245, 8, v244
	v_lshl_or_b32 v164, v246, 16, v164
	v_lshl_or_b32 v164, v247, 24, v164
	v_and_b32_e32 v203, 0xff, v164
	v_cmp_ne_u32_e64 s[98:99], 0, v203
	s_mov_b32 s100, 0
	v_mov_b32_e32 v158, v199
	v_mov_b32_e32 v159, 0
	v_mov_b32_e32 v102, 0
	v_mov_b32_e32 v103, 0
	v_mov_b32_e32 v104, 0
	v_mov_b32_e32 v105, 0
	v_mov_b32_e32 v106, 0
	v_mov_b32_e32 v107, 0
	v_mov_b32_e32 v108, 0
	v_mov_b32_e32 v109, 0
	v_mov_b32_e32 v110, 0
	v_mov_b32_e32 v111, 0
	v_mov_b32_e32 v112, 0
	v_mov_b32_e32 v113, 0
	v_mov_b32_e32 v114, 0
	v_mov_b32_e32 v115, 0
	v_mov_b32_e32 v116, 0
	v_mov_b32_e32 v117, 0
	v_mov_b32_e32 v162, v199
	v_mov_b32_e32 v163, 0
	v_mov_b32_e32 v118, 0
	v_mov_b32_e32 v119, 0
	v_mov_b32_e32 v120, 0
	v_mov_b32_e32 v121, 0
	v_mov_b32_e32 v122, 0
	v_mov_b32_e32 v123, 0
	v_mov_b32_e32 v124, 0
	v_mov_b32_e32 v125, 0
	v_mov_b32_e32 v136, 0
	v_mov_b32_e32 v137, 0
	v_mov_b32_e32 v138, 0
	v_mov_b32_e32 v139, 0
	v_mov_b32_e32 v140, 0
	v_mov_b32_e32 v141, 0
	v_mov_b32_e32 v142, 0
	v_mov_b32_e32 v143, 0

.Lsb_wd_24:
	s_bfe_u32 s22, s17, 0x40000
	s_cmp_eq_u32 s22, 0
	s_cbranch_scc1 .Lsb_sg_25
	s_lshr_b32 s22, s17, 0
	v_lshrrev_b32_e64 v203, v165, s22
	v_and_b32_e32 v203, 1, v203
	v_cmp_eq_u32_e64 s[10:11], 1, v203
	s_setprio 1
	v_mfma_f32_16x16x32_fp8_fp8 v[66:69], v[2:3], v[144:145], 0
	v_mfma_f32_16x16x32_fp8_fp8 v[70:73], v[6:7], v[144:145], 0
	v_mfma_f32_16x16x32_fp8_fp8 v[74:77], v[10:11], v[144:145], 0
	v_mfma_f32_16x16x32_fp8_fp8 v[78:81], v[14:15], v[144:145], 0
	v_mfma_f32_16x16x32_fp8_fp8 v[66:69], v[4:5], v[146:147], v[66:69]
	v_mfma_f32_16x16x32_fp8_fp8 v[70:73], v[8:9], v[146:147], v[70:73]
	v_mfma_f32_16x16x32_fp8_fp8 v[74:77], v[12:13], v[146:147], v[74:77]
	v_mfma_f32_16x16x32_fp8_fp8 v[78:81], v[16:17], v[146:147], v[78:81]
	s_setprio 0
	v_cndmask_b32_e64 v204, v200, v158, s[10:11]
	s_cmp_lg_u32 s14, s48
	s_nop 6
	s_cbranch_scc1 .Lsb_nm_26
	v_sub_u32_e32 v244, v206, v187
	v_cmp_gt_i32_e32 vcc, 0, v244
	v_cmp_gt_i32_e64 s[22:23], 1, v244
	s_nop 0
	v_cndmask_b32_e32 v66, v66, v199, vcc
	v_cndmask_b32_e64 v67, v67, v199, s[22:23]
	v_cmp_gt_i32_e32 vcc, 2, v244
	v_cmp_gt_i32_e64 s[22:23], 3, v244
	s_nop 0
	v_cndmask_b32_e32 v68, v68, v199, vcc
	v_cndmask_b32_e64 v69, v69, v199, s[22:23]
	v_sub_u32_e32 v244, v206, v187
	v_subrev_u32_e32 v244, 16, v244
	v_cmp_gt_i32_e32 vcc, 0, v244
	v_cmp_gt_i32_e64 s[22:23], 1, v244
	s_nop 0
	v_cndmask_b32_e32 v70, v70, v199, vcc
	v_cndmask_b32_e64 v71, v71, v199, s[22:23]
	v_cmp_gt_i32_e32 vcc, 2, v244
	v_cmp_gt_i32_e64 s[22:23], 3, v244
	s_nop 0
	v_cndmask_b32_e32 v72, v72, v199, vcc
	v_cndmask_b32_e64 v73, v73, v199, s[22:23]
	v_sub_u32_e32 v244, v206, v187
	v_subrev_u32_e32 v244, 32, v244
	v_cmp_gt_i32_e32 vcc, 0, v244
	v_cmp_gt_i32_e64 s[22:23], 1, v244
	s_nop 0
	v_cndmask_b32_e32 v74, v74, v199, vcc
	v_cndmask_b32_e64 v75, v75, v199, s[22:23]
	v_cmp_gt_i32_e32 vcc, 2, v244
	v_cmp_gt_i32_e64 s[22:23], 3, v244
	s_nop 0
	v_cndmask_b32_e32 v76, v76, v199, vcc
	v_cndmask_b32_e64 v77, v77, v199, s[22:23]
	v_sub_u32_e32 v244, v206, v187
	v_subrev_u32_e32 v244, 48, v244
	v_cmp_gt_i32_e32 vcc, 0, v244
	v_cmp_gt_i32_e64 s[22:23], 1, v244
	s_nop 0
	v_cndmask_b32_e32 v78, v78, v199, vcc
	v_cndmask_b32_e64 v79, v79, v199, s[22:23]
	v_cmp_gt_i32_e32 vcc, 2, v244
	v_cmp_gt_i32_e64 s[22:23], 3, v244
	s_nop 0
	v_cndmask_b32_e32 v80, v80, v199, vcc
	v_cndmask_b32_e64 v81, v81, v199, s[22:23]
.Lsb_nm_26:
	v_max3_f32 v202, v66, v67, v68
	v_max3_f32 v203, v69, v70, v71
	v_max3_f32 v202, v202, v72, v73
	v_max3_f32 v203, v203, v74, v75
	v_max3_f32 v202, v202, v76, v77
	v_max3_f32 v203, v203, v78, v79
	v_max3_f32 v202, v202, v80, v81
	v_max_f32_e32 v202, v202, v203
	v_mul_f32_e32 v202, 0x3e38aa3b, v202
	v_cndmask_b32_e64 v202, v199, v202, s[10:11]
	v_add_f32_e32 v203, 0x41000000, v158
	v_cmp_gt_f32_e32 vcc, v202, v203
	s_cbranch_vccz .Lsb_nr_27
	ds_bpermute_b32 v203, v197, v202
	s_waitcnt lgkmcnt(0)
	v_max_f32_e32 v203, v202, v203
	ds_bpermute_b32 v133, v198, v203
	s_waitcnt lgkmcnt(0)
	v_max_f32_e32 v203, v203, v133
	v_max_f32_e32 v203, v158, v203
	v_sub_f32_e32 v133, v158, v203
	v_exp_f32_e32 v133, v133
	v_mov_b32_e32 v158, v203
	s_nop 0
	v_mul_f32_e32 v159, v159, v133
	v_mul_f32_e32 v102, v102, v133
	v_mul_f32_e32 v103, v103, v133
	v_mul_f32_e32 v104, v104, v133
	v_mul_f32_e32 v105, v105, v133
	v_mul_f32_e32 v106, v106, v133
	v_mul_f32_e32 v107, v107, v133
	v_mul_f32_e32 v108, v108, v133
	v_mul_f32_e32 v109, v109, v133
	v_mul_f32_e32 v110, v110, v133
	v_mul_f32_e32 v111, v111, v133
	v_mul_f32_e32 v112, v112, v133
	v_mul_f32_e32 v113, v113, v133
	v_mul_f32_e32 v114, v114, v133
	v_mul_f32_e32 v115, v115, v133
	v_mul_f32_e32 v116, v116, v133
	v_mul_f32_e32 v117, v117, v133
	v_cndmask_b32_e64 v204, v200, v158, s[10:11]
.Lsb_nr_27:
	s_mov_b32 s22, 0x3e38aa3b
	v_fma_f32 v66, v66, s22, -v204
	v_fma_f32 v67, v67, s22, -v204
	v_fma_f32 v68, v68, s22, -v204
	v_fma_f32 v69, v69, s22, -v204
	v_fma_f32 v70, v70, s22, -v204
	v_fma_f32 v71, v71, s22, -v204
	v_fma_f32 v72, v72, s22, -v204
	v_fma_f32 v73, v73, s22, -v204
	v_fma_f32 v74, v74, s22, -v204
	v_fma_f32 v75, v75, s22, -v204
	v_fma_f32 v76, v76, s22, -v204
	v_fma_f32 v77, v77, s22, -v204
	v_fma_f32 v78, v78, s22, -v204
	v_fma_f32 v79, v79, s22, -v204
	v_fma_f32 v80, v80, s22, -v204
	v_fma_f32 v81, v81, s22, -v204
	v_exp_f32_e32 v66, v66
	v_exp_f32_e32 v67, v67
	v_exp_f32_e32 v68, v68
	v_exp_f32_e32 v69, v69
	v_exp_f32_e32 v70, v70
	v_exp_f32_e32 v71, v71
	v_exp_f32_e32 v72, v72
	v_exp_f32_e32 v73, v73
	v_exp_f32_e32 v74, v74
	v_exp_f32_e32 v75, v75
	v_exp_f32_e32 v76, v76
	v_exp_f32_e32 v77, v77
	v_exp_f32_e32 v78, v78
	v_exp_f32_e32 v79, v79
	v_exp_f32_e32 v80, v80
	v_exp_f32_e32 v81, v81
	v_add_f32_e32 v244, v66, v70
	v_add_f32_e32 v245, v67, v71
	v_add_f32_e32 v246, v68, v72
	v_add_f32_e32 v247, v69, v73
	v_add_f32_e32 v248, v74, v78
	v_add_f32_e32 v249, v75, v79
	v_add_f32_e32 v250, v76, v80
	v_add_f32_e32 v251, v77, v81
	v_add_f32_e32 v244, v244, v248
	v_add_f32_e32 v245, v245, v249
	v_add_f32_e32 v246, v246, v250
	v_add_f32_e32 v247, v247, v251
	v_cvt_pk_fp8_f32 v154, v66, v67
	v_cvt_pk_fp8_f32 v155, v70, v71
	v_cvt_pk_fp8_f32 v156, v74, v75
	v_cvt_pk_fp8_f32 v157, v78, v79
	v_add_f32_e32 v244, v244, v245
	v_cvt_pk_fp8_f32 v154, v68, v69 op_sel:[0,0,1]
	v_cvt_pk_fp8_f32 v155, v72, v73 op_sel:[0,0,1]
	v_cvt_pk_fp8_f32 v156, v76, v77 op_sel:[0,0,1]
	v_cvt_pk_fp8_f32 v157, v80, v81 op_sel:[0,0,1]
	v_add_f32_e32 v246, v246, v247
	v_add_f32_e32 v244, v244, v246
	v_add_f32_e32 v159, v159, v244
	s_setprio 1
	v_mfma_f32_16x16x32_fp8_fp8 v[102:105], v[18:19], v[154:155], v[102:105]
	v_mfma_f32_16x16x32_fp8_fp8 v[106:109], v[22:23], v[154:155], v[106:109]
	v_mfma_f32_16x16x32_fp8_fp8 v[110:113], v[26:27], v[154:155], v[110:113]
	v_mfma_f32_16x16x32_fp8_fp8 v[114:117], v[30:31], v[154:155], v[114:117]
	v_mfma_f32_16x16x32_fp8_fp8 v[102:105], v[20:21], v[156:157], v[102:105]
	v_mfma_f32_16x16x32_fp8_fp8 v[106:109], v[24:25], v[156:157], v[106:109]
	v_mfma_f32_16x16x32_fp8_fp8 v[110:113], v[28:29], v[156:157], v[110:113]
	v_mfma_f32_16x16x32_fp8_fp8 v[114:117], v[32:33], v[156:157], v[114:117]
	s_setprio 0
.Lsb_sg_25:
	s_bfe_u32 s22, s17, 0x40004
	s_cmp_eq_u32 s22, 0
	s_cbranch_scc1 .Lsb_sg_28
	s_lshr_b32 s22, s17, 4
	v_lshrrev_b32_e64 v203, v165, s22
	v_and_b32_e32 v203, 1, v203
	v_cmp_eq_u32_e64 s[10:11], 1, v203
	s_setprio 1
	v_mfma_f32_16x16x32_fp8_fp8 v[66:69], v[2:3], v[150:151], 0
	v_mfma_f32_16x16x32_fp8_fp8 v[70:73], v[6:7], v[150:151], 0
	v_mfma_f32_16x16x32_fp8_fp8 v[74:77], v[10:11], v[150:151], 0
	v_mfma_f32_16x16x32_fp8_fp8 v[78:81], v[14:15], v[150:151], 0
	v_mfma_f32_16x16x32_fp8_fp8 v[66:69], v[4:5], v[152:153], v[66:69]
	v_mfma_f32_16x16x32_fp8_fp8 v[70:73], v[8:9], v[152:153], v[70:73]
	v_mfma_f32_16x16x32_fp8_fp8 v[74:77], v[12:13], v[152:153], v[74:77]
	v_mfma_f32_16x16x32_fp8_fp8 v[78:81], v[16:17], v[152:153], v[78:81]
	s_setprio 0
	v_cndmask_b32_e64 v204, v200, v162, s[10:11]
	s_cmp_lg_u32 s14, s48
	s_nop 6
	s_cbranch_scc1 .Lsb_nm_29
	v_sub_u32_e32 v244, v206, v187
	v_subrev_u32_e32 v244, -4, v244
	v_cmp_gt_i32_e32 vcc, 0, v244
	v_cmp_gt_i32_e64 s[22:23], 1, v244
	s_nop 0
	v_cndmask_b32_e32 v66, v66, v199, vcc
	v_cndmask_b32_e64 v67, v67, v199, s[22:23]
	v_cmp_gt_i32_e32 vcc, 2, v244
	v_cmp_gt_i32_e64 s[22:23], 3, v244
	s_nop 0
	v_cndmask_b32_e32 v68, v68, v199, vcc
	v_cndmask_b32_e64 v69, v69, v199, s[22:23]
	v_sub_u32_e32 v244, v206, v187
	v_subrev_u32_e32 v244, 12, v244
	v_cmp_gt_i32_e32 vcc, 0, v244
	v_cmp_gt_i32_e64 s[22:23], 1, v244
	s_nop 0
	v_cndmask_b32_e32 v70, v70, v199, vcc
	v_cndmask_b32_e64 v71, v71, v199, s[22:23]
	v_cmp_gt_i32_e32 vcc, 2, v244
	v_cmp_gt_i32_e64 s[22:23], 3, v244
	s_nop 0
	v_cndmask_b32_e32 v72, v72, v199, vcc
	v_cndmask_b32_e64 v73, v73, v199, s[22:23]
	v_sub_u32_e32 v244, v206, v187
	v_subrev_u32_e32 v244, 28, v244
	v_cmp_gt_i32_e32 vcc, 0, v244
	v_cmp_gt_i32_e64 s[22:23], 1, v244
	s_nop 0
	v_cndmask_b32_e32 v74, v74, v199, vcc
	v_cndmask_b32_e64 v75, v75, v199, s[22:23]
	v_cmp_gt_i32_e32 vcc, 2, v244
	v_cmp_gt_i32_e64 s[22:23], 3, v244
	s_nop 0
	v_cndmask_b32_e32 v76, v76, v199, vcc
	v_cndmask_b32_e64 v77, v77, v199, s[22:23]
	v_sub_u32_e32 v244, v206, v187
	v_subrev_u32_e32 v244, 44, v244
	v_cmp_gt_i32_e32 vcc, 0, v244
	v_cmp_gt_i32_e64 s[22:23], 1, v244
	s_nop 0
	v_cndmask_b32_e32 v78, v78, v199, vcc
	v_cndmask_b32_e64 v79, v79, v199, s[22:23]
	v_cmp_gt_i32_e32 vcc, 2, v244
	v_cmp_gt_i32_e64 s[22:23], 3, v244
	s_nop 0
	v_cndmask_b32_e32 v80, v80, v199, vcc
	v_cndmask_b32_e64 v81, v81, v199, s[22:23]
.Lsb_nm_29:
	v_max3_f32 v202, v66, v67, v68
	v_max3_f32 v203, v69, v70, v71
	v_max3_f32 v202, v202, v72, v73
	v_max3_f32 v203, v203, v74, v75
	v_max3_f32 v202, v202, v76, v77
	v_max3_f32 v203, v203, v78, v79
	v_max3_f32 v202, v202, v80, v81
	v_max_f32_e32 v202, v202, v203
	v_mul_f32_e32 v202, 0x3e38aa3b, v202
	v_cndmask_b32_e64 v202, v199, v202, s[10:11]
	v_add_f32_e32 v203, 0x41000000, v162
	v_cmp_gt_f32_e32 vcc, v202, v203
	s_cbranch_vccz .Lsb_nr_30
	ds_bpermute_b32 v203, v197, v202
	s_waitcnt lgkmcnt(0)
	v_max_f32_e32 v203, v202, v203
	ds_bpermute_b32 v133, v198, v203
	s_waitcnt lgkmcnt(0)
	v_max_f32_e32 v203, v203, v133
	v_max_f32_e32 v203, v162, v203
	v_sub_f32_e32 v133, v162, v203
	v_exp_f32_e32 v133, v133
	v_mov_b32_e32 v162, v203
	s_nop 0
	v_mul_f32_e32 v163, v163, v133
	v_mul_f32_e32 v118, v118, v133
	v_mul_f32_e32 v119, v119, v133
	v_mul_f32_e32 v120, v120, v133
	v_mul_f32_e32 v121, v121, v133
	v_mul_f32_e32 v122, v122, v133
	v_mul_f32_e32 v123, v123, v133
	v_mul_f32_e32 v124, v124, v133
	v_mul_f32_e32 v125, v125, v133
	v_mul_f32_e32 v136, v136, v133
	v_mul_f32_e32 v137, v137, v133
	v_mul_f32_e32 v138, v138, v133
	v_mul_f32_e32 v139, v139, v133
	v_mul_f32_e32 v140, v140, v133
	v_mul_f32_e32 v141, v141, v133
	v_mul_f32_e32 v142, v142, v133
	v_mul_f32_e32 v143, v143, v133
	v_cndmask_b32_e64 v204, v200, v162, s[10:11]
.Lsb_nr_30:
	s_mov_b32 s22, 0x3e38aa3b
	v_fma_f32 v66, v66, s22, -v204
	v_fma_f32 v67, v67, s22, -v204
	v_fma_f32 v68, v68, s22, -v204
	v_fma_f32 v69, v69, s22, -v204
	v_fma_f32 v70, v70, s22, -v204
	v_fma_f32 v71, v71, s22, -v204
	v_fma_f32 v72, v72, s22, -v204
	v_fma_f32 v73, v73, s22, -v204
	v_fma_f32 v74, v74, s22, -v204
	v_fma_f32 v75, v75, s22, -v204
	v_fma_f32 v76, v76, s22, -v204
	v_fma_f32 v77, v77, s22, -v204
	v_fma_f32 v78, v78, s22, -v204
	v_fma_f32 v79, v79, s22, -v204
	v_fma_f32 v80, v80, s22, -v204
	v_fma_f32 v81, v81, s22, -v204
	v_exp_f32_e32 v66, v66
	v_exp_f32_e32 v67, v67
	v_exp_f32_e32 v68, v68
	v_exp_f32_e32 v69, v69
	v_exp_f32_e32 v70, v70
	v_exp_f32_e32 v71, v71
	v_exp_f32_e32 v72, v72
	v_exp_f32_e32 v73, v73
	v_exp_f32_e32 v74, v74
	v_exp_f32_e32 v75, v75
	v_exp_f32_e32 v76, v76
	v_exp_f32_e32 v77, v77
	v_exp_f32_e32 v78, v78
	v_exp_f32_e32 v79, v79
	v_exp_f32_e32 v80, v80
	v_exp_f32_e32 v81, v81
	v_add_f32_e32 v244, v66, v70
	v_add_f32_e32 v245, v67, v71
	v_add_f32_e32 v246, v68, v72
	v_add_f32_e32 v247, v69, v73
	v_add_f32_e32 v248, v74, v78
	v_add_f32_e32 v249, v75, v79
	v_add_f32_e32 v250, v76, v80
	v_add_f32_e32 v251, v77, v81
	v_add_f32_e32 v244, v244, v248
	v_add_f32_e32 v245, v245, v249
	v_add_f32_e32 v246, v246, v250
	v_add_f32_e32 v247, v247, v251
	v_cvt_pk_fp8_f32 v154, v66, v67
	v_cvt_pk_fp8_f32 v155, v70, v71
	v_cvt_pk_fp8_f32 v156, v74, v75
	v_cvt_pk_fp8_f32 v157, v78, v79
	v_add_f32_e32 v244, v244, v245
	v_cvt_pk_fp8_f32 v154, v68, v69 op_sel:[0,0,1]
	v_cvt_pk_fp8_f32 v155, v72, v73 op_sel:[0,0,1]
	v_cvt_pk_fp8_f32 v156, v76, v77 op_sel:[0,0,1]
	v_cvt_pk_fp8_f32 v157, v80, v81 op_sel:[0,0,1]
	v_add_f32_e32 v246, v246, v247
	v_add_f32_e32 v244, v244, v246
	v_add_f32_e32 v163, v163, v244
	s_setprio 1
	v_mfma_f32_16x16x32_fp8_fp8 v[118:121], v[18:19], v[154:155], v[118:121]
	v_mfma_f32_16x16x32_fp8_fp8 v[122:125], v[22:23], v[154:155], v[122:125]
	v_mfma_f32_16x16x32_fp8_fp8 v[136:139], v[26:27], v[154:155], v[136:139]
	v_mfma_f32_16x16x32_fp8_fp8 v[140:143], v[30:31], v[154:155], v[140:143]
	v_mfma_f32_16x16x32_fp8_fp8 v[118:121], v[20:21], v[156:157], v[118:121]
	v_mfma_f32_16x16x32_fp8_fp8 v[122:125], v[24:25], v[156:157], v[122:125]
	v_mfma_f32_16x16x32_fp8_fp8 v[136:139], v[28:29], v[156:157], v[136:139]
	v_mfma_f32_16x16x32_fp8_fp8 v[140:143], v[32:33], v[156:157], v[140:143]
	s_setprio 0

.Lsb_wd_39:
	s_bfe_u32 s22, s17, 0x40000
	s_cmp_eq_u32 s22, 0
	s_cbranch_scc1 .Lsb_sg_40
	s_lshr_b32 s22, s17, 0
	v_lshrrev_b32_e64 v203, v165, s22
	v_and_b32_e32 v203, 1, v203
	v_cmp_eq_u32_e64 s[10:11], 1, v203
	s_setprio 1
	v_mfma_f32_16x16x32_fp8_fp8 v[66:69], v[34:35], v[144:145], 0
	v_mfma_f32_16x16x32_fp8_fp8 v[70:73], v[38:39], v[144:145], 0
	v_mfma_f32_16x16x32_fp8_fp8 v[74:77], v[42:43], v[144:145], 0
	v_mfma_f32_16x16x32_fp8_fp8 v[78:81], v[46:47], v[144:145], 0
	v_mfma_f32_16x16x32_fp8_fp8 v[66:69], v[36:37], v[146:147], v[66:69]
	v_mfma_f32_16x16x32_fp8_fp8 v[70:73], v[40:41], v[146:147], v[70:73]
	v_mfma_f32_16x16x32_fp8_fp8 v[74:77], v[44:45], v[146:147], v[74:77]
	v_mfma_f32_16x16x32_fp8_fp8 v[78:81], v[48:49], v[146:147], v[78:81]
	s_setprio 0
	v_cndmask_b32_e64 v204, v200, v158, s[10:11]
	s_cmp_lg_u32 s14, s48
	s_nop 6
	s_cbranch_scc1 .Lsb_nm_41
	v_sub_u32_e32 v244, v206, v187
	v_cmp_gt_i32_e32 vcc, 0, v244
	v_cmp_gt_i32_e64 s[22:23], 1, v244
	s_nop 0
	v_cndmask_b32_e32 v66, v66, v199, vcc
	v_cndmask_b32_e64 v67, v67, v199, s[22:23]
	v_cmp_gt_i32_e32 vcc, 2, v244
	v_cmp_gt_i32_e64 s[22:23], 3, v244
	s_nop 0
	v_cndmask_b32_e32 v68, v68, v199, vcc
	v_cndmask_b32_e64 v69, v69, v199, s[22:23]
	v_sub_u32_e32 v244, v206, v187
	v_subrev_u32_e32 v244, 16, v244
	v_cmp_gt_i32_e32 vcc, 0, v244
	v_cmp_gt_i32_e64 s[22:23], 1, v244
	s_nop 0
	v_cndmask_b32_e32 v70, v70, v199, vcc
	v_cndmask_b32_e64 v71, v71, v199, s[22:23]
	v_cmp_gt_i32_e32 vcc, 2, v244
	v_cmp_gt_i32_e64 s[22:23], 3, v244
	s_nop 0
	v_cndmask_b32_e32 v72, v72, v199, vcc
	v_cndmask_b32_e64 v73, v73, v199, s[22:23]
	v_sub_u32_e32 v244, v206, v187
	v_subrev_u32_e32 v244, 32, v244
	v_cmp_gt_i32_e32 vcc, 0, v244
	v_cmp_gt_i32_e64 s[22:23], 1, v244
	s_nop 0
	v_cndmask_b32_e32 v74, v74, v199, vcc
	v_cndmask_b32_e64 v75, v75, v199, s[22:23]
	v_cmp_gt_i32_e32 vcc, 2, v244
	v_cmp_gt_i32_e64 s[22:23], 3, v244
	s_nop 0
	v_cndmask_b32_e32 v76, v76, v199, vcc
	v_cndmask_b32_e64 v77, v77, v199, s[22:23]
	v_sub_u32_e32 v244, v206, v187
	v_subrev_u32_e32 v244, 48, v244
	v_cmp_gt_i32_e32 vcc, 0, v244
	v_cmp_gt_i32_e64 s[22:23], 1, v244
	s_nop 0
	v_cndmask_b32_e32 v78, v78, v199, vcc
	v_cndmask_b32_e64 v79, v79, v199, s[22:23]
	v_cmp_gt_i32_e32 vcc, 2, v244
	v_cmp_gt_i32_e64 s[22:23], 3, v244
	s_nop 0
	v_cndmask_b32_e32 v80, v80, v199, vcc
	v_cndmask_b32_e64 v81, v81, v199, s[22:23]

.Lsb_nr_42:
	s_mov_b32 s22, 0x3e38aa3b
	v_fma_f32 v66, v66, s22, -v204
	v_fma_f32 v67, v67, s22, -v204
	v_fma_f32 v68, v68, s22, -v204
	v_fma_f32 v69, v69, s22, -v204
	v_fma_f32 v70, v70, s22, -v204
	v_fma_f32 v71, v71, s22, -v204
	v_fma_f32 v72, v72, s22, -v204
	v_fma_f32 v73, v73, s22, -v204
	v_fma_f32 v74, v74, s22, -v204
	v_fma_f32 v75, v75, s22, -v204
	v_fma_f32 v76, v76, s22, -v204
	v_fma_f32 v77, v77, s22, -v204
	v_fma_f32 v78, v78, s22, -v204
	v_fma_f32 v79, v79, s22, -v204
	v_fma_f32 v80, v80, s22, -v204
	v_fma_f32 v81, v81, s22, -v204
	v_exp_f32_e32 v66, v66
	v_exp_f32_e32 v67, v67
	v_exp_f32_e32 v68, v68
	v_exp_f32_e32 v69, v69
	v_exp_f32_e32 v70, v70
	v_exp_f32_e32 v71, v71
	v_exp_f32_e32 v72, v72
	v_exp_f32_e32 v73, v73
	v_exp_f32_e32 v74, v74
	v_exp_f32_e32 v75, v75
	v_exp_f32_e32 v76, v76
	v_exp_f32_e32 v77, v77
	v_exp_f32_e32 v78, v78
	v_exp_f32_e32 v79, v79
	v_exp_f32_e32 v80, v80
	v_exp_f32_e32 v81, v81
	v_add_f32_e32 v244, v66, v70
	v_add_f32_e32 v245, v67, v71
	v_add_f32_e32 v246, v68, v72
	v_add_f32_e32 v247, v69, v73
	v_add_f32_e32 v248, v74, v78
	v_add_f32_e32 v249, v75, v79
	v_add_f32_e32 v250, v76, v80
	v_add_f32_e32 v251, v77, v81
	v_add_f32_e32 v244, v244, v248
	v_add_f32_e32 v245, v245, v249
	v_add_f32_e32 v246, v246, v250
	v_add_f32_e32 v247, v247, v251
	v_cvt_pk_fp8_f32 v154, v66, v67
	v_cvt_pk_fp8_f32 v155, v70, v71
	v_cvt_pk_fp8_f32 v156, v74, v75
	v_cvt_pk_fp8_f32 v157, v78, v79
	v_add_f32_e32 v244, v244, v245
	v_cvt_pk_fp8_f32 v154, v68, v69 op_sel:[0,0,1]
	v_cvt_pk_fp8_f32 v155, v72, v73 op_sel:[0,0,1]
	v_cvt_pk_fp8_f32 v156, v76, v77 op_sel:[0,0,1]
	v_cvt_pk_fp8_f32 v157, v80, v81 op_sel:[0,0,1]
	v_add_f32_e32 v246, v246, v247
	v_add_f32_e32 v244, v244, v246
	v_add_f32_e32 v159, v159, v244
	s_setprio 1
	v_mfma_f32_16x16x32_fp8_fp8 v[102:105], v[50:51], v[154:155], v[102:105]
	v_mfma_f32_16x16x32_fp8_fp8 v[106:109], v[54:55], v[154:155], v[106:109]
	v_mfma_f32_16x16x32_fp8_fp8 v[110:113], v[58:59], v[154:155], v[110:113]
	v_mfma_f32_16x16x32_fp8_fp8 v[114:117], v[62:63], v[154:155], v[114:117]
	v_mfma_f32_16x16x32_fp8_fp8 v[102:105], v[52:53], v[156:157], v[102:105]
	v_mfma_f32_16x16x32_fp8_fp8 v[106:109], v[56:57], v[156:157], v[106:109]
	v_mfma_f32_16x16x32_fp8_fp8 v[110:113], v[60:61], v[156:157], v[110:113]
	v_mfma_f32_16x16x32_fp8_fp8 v[114:117], v[64:65], v[156:157], v[114:117]
	s_setprio 0
.Lsb_sg_40:
	s_bfe_u32 s22, s17, 0x40004
	s_cmp_eq_u32 s22, 0
	s_cbranch_scc1 .Lsb_sg_43
	s_lshr_b32 s22, s17, 4
	v_lshrrev_b32_e64 v203, v165, s22
	v_and_b32_e32 v203, 1, v203
	v_cmp_eq_u32_e64 s[10:11], 1, v203
	s_setprio 1
	v_mfma_f32_16x16x32_fp8_fp8 v[66:69], v[34:35], v[150:151], 0
	v_mfma_f32_16x16x32_fp8_fp8 v[70:73], v[38:39], v[150:151], 0
	v_mfma_f32_16x16x32_fp8_fp8 v[74:77], v[42:43], v[150:151], 0
	v_mfma_f32_16x16x32_fp8_fp8 v[78:81], v[46:47], v[150:151], 0
	v_mfma_f32_16x16x32_fp8_fp8 v[66:69], v[36:37], v[152:153], v[66:69]
	v_mfma_f32_16x16x32_fp8_fp8 v[70:73], v[40:41], v[152:153], v[70:73]
	v_mfma_f32_16x16x32_fp8_fp8 v[74:77], v[44:45], v[152:153], v[74:77]
	v_mfma_f32_16x16x32_fp8_fp8 v[78:81], v[48:49], v[152:153], v[78:81]
	s_setprio 0
	v_cndmask_b32_e64 v204, v200, v162, s[10:11]
	s_cmp_lg_u32 s14, s48
	s_nop 6
	s_cbranch_scc1 .Lsb_nm_44
	v_sub_u32_e32 v244, v206, v187
	v_subrev_u32_e32 v244, -4, v244
	v_cmp_gt_i32_e32 vcc, 0, v244
	v_cmp_gt_i32_e64 s[22:23], 1, v244
	s_nop 0
	v_cndmask_b32_e32 v66, v66, v199, vcc
	v_cndmask_b32_e64 v67, v67, v199, s[22:23]
	v_cmp_gt_i32_e32 vcc, 2, v244
	v_cmp_gt_i32_e64 s[22:23], 3, v244
	s_nop 0
	v_cndmask_b32_e32 v68, v68, v199, vcc
	v_cndmask_b32_e64 v69, v69, v199, s[22:23]
	v_sub_u32_e32 v244, v206, v187
	v_subrev_u32_e32 v244, 12, v244
	v_cmp_gt_i32_e32 vcc, 0, v244
	v_cmp_gt_i32_e64 s[22:23], 1, v244
	s_nop 0
	v_cndmask_b32_e32 v70, v70, v199, vcc
	v_cndmask_b32_e64 v71, v71, v199, s[22:23]
	v_cmp_gt_i32_e32 vcc, 2, v244
	v_cmp_gt_i32_e64 s[22:23], 3, v244
	s_nop 0
	v_cndmask_b32_e32 v72, v72, v199, vcc
	v_cndmask_b32_e64 v73, v73, v199, s[22:23]
	v_sub_u32_e32 v244, v206, v187
	v_subrev_u32_e32 v244, 28, v244
	v_cmp_gt_i32_e32 vcc, 0, v244
	v_cmp_gt_i32_e64 s[22:23], 1, v244
	s_nop 0
	v_cndmask_b32_e32 v74, v74, v199, vcc
	v_cndmask_b32_e64 v75, v75, v199, s[22:23]
	v_cmp_gt_i32_e32 vcc, 2, v244
	v_cmp_gt_i32_e64 s[22:23], 3, v244
	s_nop 0
	v_cndmask_b32_e32 v76, v76, v199, vcc
	v_cndmask_b32_e64 v77, v77, v199, s[22:23]
	v_sub_u32_e32 v244, v206, v187
	v_subrev_u32_e32 v244, 44, v244
	v_cmp_gt_i32_e32 vcc, 0, v244
	v_cmp_gt_i32_e64 s[22:23], 1, v244
	s_nop 0
	v_cndmask_b32_e32 v78, v78, v199, vcc
	v_cndmask_b32_e64 v79, v79, v199, s[22:23]
	v_cmp_gt_i32_e32 vcc, 2, v244
	v_cmp_gt_i32_e64 s[22:23], 3, v244
	s_nop 0
	v_cndmask_b32_e32 v80, v80, v199, vcc
	v_cndmask_b32_e64 v81, v81, v199, s[22:23]

.Lsb_nr_45:
	s_mov_b32 s22, 0x3e38aa3b
	v_fma_f32 v66, v66, s22, -v204
	v_fma_f32 v67, v67, s22, -v204
	v_fma_f32 v68, v68, s22, -v204
	v_fma_f32 v69, v69, s22, -v204
	v_fma_f32 v70, v70, s22, -v204
	v_fma_f32 v71, v71, s22, -v204
	v_fma_f32 v72, v72, s22, -v204
	v_fma_f32 v73, v73, s22, -v204
	v_fma_f32 v74, v74, s22, -v204
	v_fma_f32 v75, v75, s22, -v204
	v_fma_f32 v76, v76, s22, -v204
	v_fma_f32 v77, v77, s22, -v204
	v_fma_f32 v78, v78, s22, -v204
	v_fma_f32 v79, v79, s22, -v204
	v_fma_f32 v80, v80, s22, -v204
	v_fma_f32 v81, v81, s22, -v204
	v_exp_f32_e32 v66, v66
	v_exp_f32_e32 v67, v67
	v_exp_f32_e32 v68, v68
	v_exp_f32_e32 v69, v69
	v_exp_f32_e32 v70, v70
	v_exp_f32_e32 v71, v71
	v_exp_f32_e32 v72, v72
	v_exp_f32_e32 v73, v73
	v_exp_f32_e32 v74, v74
	v_exp_f32_e32 v75, v75
	v_exp_f32_e32 v76, v76
	v_exp_f32_e32 v77, v77
	v_exp_f32_e32 v78, v78
	v_exp_f32_e32 v79, v79
	v_exp_f32_e32 v80, v80
	v_exp_f32_e32 v81, v81
	v_add_f32_e32 v244, v66, v70
	v_add_f32_e32 v245, v67, v71
	v_add_f32_e32 v246, v68, v72
	v_add_f32_e32 v247, v69, v73
	v_add_f32_e32 v248, v74, v78
	v_add_f32_e32 v249, v75, v79
	v_add_f32_e32 v250, v76, v80
	v_add_f32_e32 v251, v77, v81
	v_add_f32_e32 v244, v244, v248
	v_add_f32_e32 v245, v245, v249
	v_add_f32_e32 v246, v246, v250
	v_add_f32_e32 v247, v247, v251
	v_cvt_pk_fp8_f32 v154, v66, v67
	v_cvt_pk_fp8_f32 v155, v70, v71
	v_cvt_pk_fp8_f32 v156, v74, v75
	v_cvt_pk_fp8_f32 v157, v78, v79
	v_add_f32_e32 v244, v244, v245
	v_cvt_pk_fp8_f32 v154, v68, v69 op_sel:[0,0,1]
	v_cvt_pk_fp8_f32 v155, v72, v73 op_sel:[0,0,1]
	v_cvt_pk_fp8_f32 v156, v76, v77 op_sel:[0,0,1]
	v_cvt_pk_fp8_f32 v157, v80, v81 op_sel:[0,0,1]
	v_add_f32_e32 v246, v246, v247
	v_add_f32_e32 v244, v244, v246
	v_add_f32_e32 v163, v163, v244
	s_setprio 1
	v_mfma_f32_16x16x32_fp8_fp8 v[118:121], v[50:51], v[154:155], v[118:121]
	v_mfma_f32_16x16x32_fp8_fp8 v[122:125], v[54:55], v[154:155], v[122:125]
	v_mfma_f32_16x16x32_fp8_fp8 v[136:139], v[58:59], v[154:155], v[136:139]
	v_mfma_f32_16x16x32_fp8_fp8 v[140:143], v[62:63], v[154:155], v[140:143]
	v_mfma_f32_16x16x32_fp8_fp8 v[118:121], v[52:53], v[156:157], v[118:121]
	v_mfma_f32_16x16x32_fp8_fp8 v[122:125], v[56:57], v[156:157], v[122:125]
	v_mfma_f32_16x16x32_fp8_fp8 v[136:139], v[60:61], v[156:157], v[136:139]
	v_mfma_f32_16x16x32_fp8_fp8 v[140:143], v[64:65], v[156:157], v[140:143]
	s_setprio 0

.Lsb_wd_54:
	s_bfe_u32 s22, s17, 0x40000
	s_cmp_eq_u32 s22, 0
	s_cbranch_scc1 .Lsb_sg_55
	s_lshr_b32 s22, s17, 0
	v_lshrrev_b32_e64 v203, v165, s22
	v_and_b32_e32 v203, 1, v203
	v_cmp_eq_u32_e64 s[10:11], 1, v203
	s_setprio 1
	v_mfma_f32_16x16x32_fp8_fp8 v[66:69], v[212:213], v[144:145], 0
	v_mfma_f32_16x16x32_fp8_fp8 v[70:73], v[216:217], v[144:145], 0
	v_mfma_f32_16x16x32_fp8_fp8 v[74:77], v[220:221], v[144:145], 0
	v_mfma_f32_16x16x32_fp8_fp8 v[78:81], v[224:225], v[144:145], 0
	v_mfma_f32_16x16x32_fp8_fp8 v[66:69], v[214:215], v[146:147], v[66:69]
	v_mfma_f32_16x16x32_fp8_fp8 v[70:73], v[218:219], v[146:147], v[70:73]
	v_mfma_f32_16x16x32_fp8_fp8 v[74:77], v[222:223], v[146:147], v[74:77]
	v_mfma_f32_16x16x32_fp8_fp8 v[78:81], v[226:227], v[146:147], v[78:81]
	s_setprio 0
	v_cndmask_b32_e64 v204, v200, v158, s[10:11]
	s_cmp_lg_u32 s14, s48
	s_nop 6
	s_cbranch_scc1 .Lsb_nm_56
	v_sub_u32_e32 v244, v206, v187
	v_cmp_gt_i32_e32 vcc, 0, v244
	v_cmp_gt_i32_e64 s[22:23], 1, v244
	s_nop 0
	v_cndmask_b32_e32 v66, v66, v199, vcc
	v_cndmask_b32_e64 v67, v67, v199, s[22:23]
	v_cmp_gt_i32_e32 vcc, 2, v244
	v_cmp_gt_i32_e64 s[22:23], 3, v244
	s_nop 0
	v_cndmask_b32_e32 v68, v68, v199, vcc
	v_cndmask_b32_e64 v69, v69, v199, s[22:23]
	v_sub_u32_e32 v244, v206, v187
	v_subrev_u32_e32 v244, 16, v244
	v_cmp_gt_i32_e32 vcc, 0, v244
	v_cmp_gt_i32_e64 s[22:23], 1, v244
	s_nop 0
	v_cndmask_b32_e32 v70, v70, v199, vcc
	v_cndmask_b32_e64 v71, v71, v199, s[22:23]
	v_cmp_gt_i32_e32 vcc, 2, v244
	v_cmp_gt_i32_e64 s[22:23], 3, v244
	s_nop 0
	v_cndmask_b32_e32 v72, v72, v199, vcc
	v_cndmask_b32_e64 v73, v73, v199, s[22:23]
	v_sub_u32_e32 v244, v206, v187
	v_subrev_u32_e32 v244, 32, v244
	v_cmp_gt_i32_e32 vcc, 0, v244
	v_cmp_gt_i32_e64 s[22:23], 1, v244
	s_nop 0
	v_cndmask_b32_e32 v74, v74, v199, vcc
	v_cndmask_b32_e64 v75, v75, v199, s[22:23]
	v_cmp_gt_i32_e32 vcc, 2, v244
	v_cmp_gt_i32_e64 s[22:23], 3, v244
	s_nop 0
	v_cndmask_b32_e32 v76, v76, v199, vcc
	v_cndmask_b32_e64 v77, v77, v199, s[22:23]
	v_sub_u32_e32 v244, v206, v187
	v_subrev_u32_e32 v244, 48, v244
	v_cmp_gt_i32_e32 vcc, 0, v244
	v_cmp_gt_i32_e64 s[22:23], 1, v244
	s_nop 0
	v_cndmask_b32_e32 v78, v78, v199, vcc
	v_cndmask_b32_e64 v79, v79, v199, s[22:23]
	v_cmp_gt_i32_e32 vcc, 2, v244
	v_cmp_gt_i32_e64 s[22:23], 3, v244
	s_nop 0
	v_cndmask_b32_e32 v80, v80, v199, vcc
	v_cndmask_b32_e64 v81, v81, v199, s[22:23]

.Lsb_nr_57:
	s_mov_b32 s22, 0x3e38aa3b
	v_fma_f32 v66, v66, s22, -v204
	v_fma_f32 v67, v67, s22, -v204
	v_fma_f32 v68, v68, s22, -v204
	v_fma_f32 v69, v69, s22, -v204
	v_fma_f32 v70, v70, s22, -v204
	v_fma_f32 v71, v71, s22, -v204
	v_fma_f32 v72, v72, s22, -v204
	v_fma_f32 v73, v73, s22, -v204
	v_fma_f32 v74, v74, s22, -v204
	v_fma_f32 v75, v75, s22, -v204
	v_fma_f32 v76, v76, s22, -v204
	v_fma_f32 v77, v77, s22, -v204
	v_fma_f32 v78, v78, s22, -v204
	v_fma_f32 v79, v79, s22, -v204
	v_fma_f32 v80, v80, s22, -v204
	v_fma_f32 v81, v81, s22, -v204
	v_exp_f32_e32 v66, v66
	v_exp_f32_e32 v67, v67
	v_exp_f32_e32 v68, v68
	v_exp_f32_e32 v69, v69
	v_exp_f32_e32 v70, v70
	v_exp_f32_e32 v71, v71
	v_exp_f32_e32 v72, v72
	v_exp_f32_e32 v73, v73
	v_exp_f32_e32 v74, v74
	v_exp_f32_e32 v75, v75
	v_exp_f32_e32 v76, v76
	v_exp_f32_e32 v77, v77
	v_exp_f32_e32 v78, v78
	v_exp_f32_e32 v79, v79
	v_exp_f32_e32 v80, v80
	v_exp_f32_e32 v81, v81
	v_add_f32_e32 v244, v66, v70
	v_add_f32_e32 v245, v67, v71
	v_add_f32_e32 v246, v68, v72
	v_add_f32_e32 v247, v69, v73
	v_add_f32_e32 v248, v74, v78
	v_add_f32_e32 v249, v75, v79
	v_add_f32_e32 v250, v76, v80
	v_add_f32_e32 v251, v77, v81
	v_add_f32_e32 v244, v244, v248
	v_add_f32_e32 v245, v245, v249
	v_add_f32_e32 v246, v246, v250
	v_add_f32_e32 v247, v247, v251
	v_cvt_pk_fp8_f32 v154, v66, v67
	v_cvt_pk_fp8_f32 v155, v70, v71
	v_cvt_pk_fp8_f32 v156, v74, v75
	v_cvt_pk_fp8_f32 v157, v78, v79
	v_add_f32_e32 v244, v244, v245
	v_cvt_pk_fp8_f32 v154, v68, v69 op_sel:[0,0,1]
	v_cvt_pk_fp8_f32 v155, v72, v73 op_sel:[0,0,1]
	v_cvt_pk_fp8_f32 v156, v76, v77 op_sel:[0,0,1]
	v_cvt_pk_fp8_f32 v157, v80, v81 op_sel:[0,0,1]
	v_add_f32_e32 v246, v246, v247
	v_add_f32_e32 v244, v244, v246
	v_add_f32_e32 v159, v159, v244
	s_setprio 1
	v_mfma_f32_16x16x32_fp8_fp8 v[102:105], v[228:229], v[154:155], v[102:105]
	v_mfma_f32_16x16x32_fp8_fp8 v[106:109], v[232:233], v[154:155], v[106:109]
	v_mfma_f32_16x16x32_fp8_fp8 v[110:113], v[236:237], v[154:155], v[110:113]
	v_mfma_f32_16x16x32_fp8_fp8 v[114:117], v[240:241], v[154:155], v[114:117]
	v_mfma_f32_16x16x32_fp8_fp8 v[102:105], v[230:231], v[156:157], v[102:105]
	v_mfma_f32_16x16x32_fp8_fp8 v[106:109], v[234:235], v[156:157], v[106:109]
	v_mfma_f32_16x16x32_fp8_fp8 v[110:113], v[238:239], v[156:157], v[110:113]
	v_mfma_f32_16x16x32_fp8_fp8 v[114:117], v[242:243], v[156:157], v[114:117]
	s_setprio 0
.Lsb_sg_55:
	s_bfe_u32 s22, s17, 0x40004
	s_cmp_eq_u32 s22, 0
	s_cbranch_scc1 .Lsb_sg_58
	s_lshr_b32 s22, s17, 4
	v_lshrrev_b32_e64 v203, v165, s22
	v_and_b32_e32 v203, 1, v203
	v_cmp_eq_u32_e64 s[10:11], 1, v203
	s_setprio 1
	v_mfma_f32_16x16x32_fp8_fp8 v[66:69], v[212:213], v[150:151], 0
	v_mfma_f32_16x16x32_fp8_fp8 v[70:73], v[216:217], v[150:151], 0
	v_mfma_f32_16x16x32_fp8_fp8 v[74:77], v[220:221], v[150:151], 0
	v_mfma_f32_16x16x32_fp8_fp8 v[78:81], v[224:225], v[150:151], 0
	v_mfma_f32_16x16x32_fp8_fp8 v[66:69], v[214:215], v[152:153], v[66:69]
	v_mfma_f32_16x16x32_fp8_fp8 v[70:73], v[218:219], v[152:153], v[70:73]
	v_mfma_f32_16x16x32_fp8_fp8 v[74:77], v[222:223], v[152:153], v[74:77]
	v_mfma_f32_16x16x32_fp8_fp8 v[78:81], v[226:227], v[152:153], v[78:81]
	s_setprio 0
	v_cndmask_b32_e64 v204, v200, v162, s[10:11]
	s_cmp_lg_u32 s14, s48
	s_nop 6
	s_cbranch_scc1 .Lsb_nm_59
	v_sub_u32_e32 v244, v206, v187
	v_subrev_u32_e32 v244, -4, v244
	v_cmp_gt_i32_e32 vcc, 0, v244
	v_cmp_gt_i32_e64 s[22:23], 1, v244
	s_nop 0
	v_cndmask_b32_e32 v66, v66, v199, vcc
	v_cndmask_b32_e64 v67, v67, v199, s[22:23]
	v_cmp_gt_i32_e32 vcc, 2, v244
	v_cmp_gt_i32_e64 s[22:23], 3, v244
	s_nop 0
	v_cndmask_b32_e32 v68, v68, v199, vcc
	v_cndmask_b32_e64 v69, v69, v199, s[22:23]
	v_sub_u32_e32 v244, v206, v187
	v_subrev_u32_e32 v244, 12, v244
	v_cmp_gt_i32_e32 vcc, 0, v244
	v_cmp_gt_i32_e64 s[22:23], 1, v244
	s_nop 0
	v_cndmask_b32_e32 v70, v70, v199, vcc
	v_cndmask_b32_e64 v71, v71, v199, s[22:23]
	v_cmp_gt_i32_e32 vcc, 2, v244
	v_cmp_gt_i32_e64 s[22:23], 3, v244
	s_nop 0
	v_cndmask_b32_e32 v72, v72, v199, vcc
	v_cndmask_b32_e64 v73, v73, v199, s[22:23]
	v_sub_u32_e32 v244, v206, v187
	v_subrev_u32_e32 v244, 28, v244
	v_cmp_gt_i32_e32 vcc, 0, v244
	v_cmp_gt_i32_e64 s[22:23], 1, v244
	s_nop 0
	v_cndmask_b32_e32 v74, v74, v199, vcc
	v_cndmask_b32_e64 v75, v75, v199, s[22:23]
	v_cmp_gt_i32_e32 vcc, 2, v244
	v_cmp_gt_i32_e64 s[22:23], 3, v244
	s_nop 0
	v_cndmask_b32_e32 v76, v76, v199, vcc
	v_cndmask_b32_e64 v77, v77, v199, s[22:23]
	v_sub_u32_e32 v244, v206, v187
	v_subrev_u32_e32 v244, 44, v244
	v_cmp_gt_i32_e32 vcc, 0, v244
	v_cmp_gt_i32_e64 s[22:23], 1, v244
	s_nop 0
	v_cndmask_b32_e32 v78, v78, v199, vcc
	v_cndmask_b32_e64 v79, v79, v199, s[22:23]
	v_cmp_gt_i32_e32 vcc, 2, v244
	v_cmp_gt_i32_e64 s[22:23], 3, v244
	s_nop 0
	v_cndmask_b32_e32 v80, v80, v199, vcc
	v_cndmask_b32_e64 v81, v81, v199, s[22:23]

.Lsb_nr_60:
	s_mov_b32 s22, 0x3e38aa3b
	v_fma_f32 v66, v66, s22, -v204
	v_fma_f32 v67, v67, s22, -v204
	v_fma_f32 v68, v68, s22, -v204
	v_fma_f32 v69, v69, s22, -v204
	v_fma_f32 v70, v70, s22, -v204
	v_fma_f32 v71, v71, s22, -v204
	v_fma_f32 v72, v72, s22, -v204
	v_fma_f32 v73, v73, s22, -v204
	v_fma_f32 v74, v74, s22, -v204
	v_fma_f32 v75, v75, s22, -v204
	v_fma_f32 v76, v76, s22, -v204
	v_fma_f32 v77, v77, s22, -v204
	v_fma_f32 v78, v78, s22, -v204
	v_fma_f32 v79, v79, s22, -v204
	v_fma_f32 v80, v80, s22, -v204
	v_fma_f32 v81, v81, s22, -v204
	v_exp_f32_e32 v66, v66
	v_exp_f32_e32 v67, v67
	v_exp_f32_e32 v68, v68
	v_exp_f32_e32 v69, v69
	v_exp_f32_e32 v70, v70
	v_exp_f32_e32 v71, v71
	v_exp_f32_e32 v72, v72
	v_exp_f32_e32 v73, v73
	v_exp_f32_e32 v74, v74
	v_exp_f32_e32 v75, v75
	v_exp_f32_e32 v76, v76
	v_exp_f32_e32 v77, v77
	v_exp_f32_e32 v78, v78
	v_exp_f32_e32 v79, v79
	v_exp_f32_e32 v80, v80
	v_exp_f32_e32 v81, v81
	v_add_f32_e32 v244, v66, v70
	v_add_f32_e32 v245, v67, v71
	v_add_f32_e32 v246, v68, v72
	v_add_f32_e32 v247, v69, v73
	v_add_f32_e32 v248, v74, v78
	v_add_f32_e32 v249, v75, v79
	v_add_f32_e32 v250, v76, v80
	v_add_f32_e32 v251, v77, v81
	v_add_f32_e32 v244, v244, v248
	v_add_f32_e32 v245, v245, v249
	v_add_f32_e32 v246, v246, v250
	v_add_f32_e32 v247, v247, v251
	v_cvt_pk_fp8_f32 v154, v66, v67
	v_cvt_pk_fp8_f32 v155, v70, v71
	v_cvt_pk_fp8_f32 v156, v74, v75
	v_cvt_pk_fp8_f32 v157, v78, v79
	v_add_f32_e32 v244, v244, v245
	v_cvt_pk_fp8_f32 v154, v68, v69 op_sel:[0,0,1]
	v_cvt_pk_fp8_f32 v155, v72, v73 op_sel:[0,0,1]
	v_cvt_pk_fp8_f32 v156, v76, v77 op_sel:[0,0,1]
	v_cvt_pk_fp8_f32 v157, v80, v81 op_sel:[0,0,1]
	v_add_f32_e32 v246, v246, v247
	v_add_f32_e32 v244, v244, v246
	v_add_f32_e32 v163, v163, v244
	s_setprio 1
	v_mfma_f32_16x16x32_fp8_fp8 v[118:121], v[228:229], v[154:155], v[118:121]
	v_mfma_f32_16x16x32_fp8_fp8 v[122:125], v[232:233], v[154:155], v[122:125]
	v_mfma_f32_16x16x32_fp8_fp8 v[136:139], v[236:237], v[154:155], v[136:139]
	v_mfma_f32_16x16x32_fp8_fp8 v[140:143], v[240:241], v[154:155], v[140:143]
	v_mfma_f32_16x16x32_fp8_fp8 v[118:121], v[230:231], v[156:157], v[118:121]
	v_mfma_f32_16x16x32_fp8_fp8 v[122:125], v[234:235], v[156:157], v[122:125]
	v_mfma_f32_16x16x32_fp8_fp8 v[136:139], v[238:239], v[156:157], v[136:139]
	v_mfma_f32_16x16x32_fp8_fp8 v[140:143], v[242:243], v[156:157], v[140:143]
	s_setprio 0
